# in-proj GEMM epilogues: lanes permuted (ds_bpermute) so adjacent lanes store adjacent 16B pieces of a 128B line (coalesced full-line stores)
# speedup vs baseline: 1.0147x; 1.0147x over previous
; #define PG8_STAGE(bufoff, gbase, voff) do { _Pragma("unroll") for (int _i = 0; _i < 2; ++_i) \
;         __builtin_amdgcn_global_load_lds((const unsigned*)((const char*)(gbase) + (voff)[_i]), (LAS unsigned*)(lds + (bufoff) + ldsw + _i * 8192), 16, 0, 0); } while (0)
; #define PG8_LDA(dst, b, h) do { _Pragma("unroll") for (int m = 0; m < 4; ++m) _Pragma("unroll") for (int k = 0; k < 2; ++k) dst[m][k] = *(const LAS bf16x8*)(lds + PG8_SA(b, h) + aoff + m * 2048 + k * 1024); } while (0)
; #define PG8_LDB(dst, b, h) do { _Pragma("unroll") for (int n = 0; n < 2; ++n) _Pragma("unroll") for (int k = 0; k < 2; ++k) dst[n][k] = *(const LAS bf16x8*)(lds + PG8_SB(b, h) + boff + n * 2048 + k * 1024); } while (0)
; #define PG8_MMA(ai, bj, At, Bt) do { __builtin_amdgcn_s_setprio(1); _Pragma("unroll") for (int m = 0; m < 4; ++m) _Pragma("unroll") for (int n = 0; n < 2; ++n) _Pragma("unroll") for (int k = 0; k < 2; ++k) \
;         acc[ai][bj][m][n] = __builtin_amdgcn_mfma_f32_16x16x32_bf16(Bt[n][k], At[m][k], acc[ai][bj][m][n], 0, 0, 0); __builtin_amdgcn_s_setprio(0); } while (0)
; #define PG8_WAIT_L(n) asm volatile("s_waitcnt lgkmcnt(" #n ")" ::: "memory")
; #define PG8_BAR __builtin_amdgcn_s_barrier()
; #define PG8_SCHED __builtin_amdgcn_sched_barrier(0)
; template <class Epi, class Sched>
; DI void gemm_phase(LAS unsigned char* lds, const Gemm g, const Sched& S, const Epi& E) {
;     ...
;             PG8_LDB(B0, 0, 0); PG8_SCHED; PG8_LDA(At, 0, 0); PG8_STAGE(PG8_SA(1, 1), a1 + hstep, voffA);
;             PG8_WAIT_L(8); PG8_BAR; PG8_WAIT_L(0); PG8_MMA(0, 0, At, B0); PG8_BAR; PG8_SCHED;
;             PG8_LDB(B1, 0, 1); PG8_STAGE(PG8_SB(0, 0), b2, voffB);
;             PG8_BAR; PG8_WAIT_L(0); PG8_MMA(0, 1, At, B1); PG8_BAR;
;             PG8_LDA(At, 0, 1); PG8_STAGE(PG8_SA(0, 0), a2, voffA);
;             PG8_BAR; PG8_WAIT_L(0); PG8_MMA(1, 0, At, B0); PG8_BAR; PG8_SCHED;
.LBB0_130:
	ds_read_b128 v[156:159], v149
	ds_read_b128 v[160:163], v149 offset:1024
	ds_read_b128 v[164:167], v149 offset:2048
	ds_read_b128 v[168:171], v149 offset:3072
	s_add_u32 s26, s24, 0xfffc0080
	s_addc_u32 s27, s25, -1
	s_cmp_eq_u32 s45, 12
	s_cselect_b32 s29, s19, s27
	s_cselect_b32 s28, s41, s26
	s_cselect_b32 s27, s11, s44
	s_cselect_b32 s26, s42, s43
	v_lshl_add_u64 v[204:205], s[24:25], 0, v[138:139]
	s_add_i32 m0, s9, 0xc000
	ds_read_b128 v[172:175], v150
	ds_read_b128 v[176:179], v150 offset:1024
	ds_read_b128 v[180:183], v150 offset:2048
	ds_read_b128 v[184:187], v150 offset:3072
	ds_read_b128 v[188:191], v150 offset:4096
	ds_read_b128 v[192:195], v150 offset:5120
	ds_read_b128 v[196:199], v150 offset:6144
	ds_read_b128 v[200:203], v150 offset:7168
	global_load_lds_dwordx4 v[204:205], off
	v_lshl_add_u64 v[204:205], s[24:25], 0, v[140:141]
	s_add_i32 m0, s9, 0xe000
	s_nop 0
	global_load_lds_dwordx4 v[204:205], off
	s_waitcnt lgkmcnt(8)
	s_barrier
	s_waitcnt lgkmcnt(0)
	s_setprio 1
	s_waitcnt lgkmcnt(0)
	v_mfma_f32_16x16x32_bf16 v[126:129], v[156:159], v[172:175], v[126:129]
	v_mfma_f32_16x16x32_bf16 v[122:125], v[164:167], v[172:175], v[122:125]
	v_mfma_f32_16x16x32_bf16 v[118:121], v[156:159], v[180:183], v[118:121]
	v_mfma_f32_16x16x32_bf16 v[114:117], v[164:167], v[180:183], v[114:117]
	v_mfma_f32_16x16x32_bf16 v[102:105], v[156:159], v[188:191], v[102:105]
	v_mfma_f32_16x16x32_bf16 v[98:101], v[164:167], v[188:191], v[98:101]
	v_mfma_f32_16x16x32_bf16 v[86:89], v[156:159], v[196:199], v[86:89]
	v_mfma_f32_16x16x32_bf16 v[82:85], v[164:167], v[196:199], v[82:85]
	v_mfma_f32_16x16x32_bf16 v[126:129], v[160:163], v[176:179], v[126:129]
	v_mfma_f32_16x16x32_bf16 v[122:125], v[168:171], v[176:179], v[122:125]
	v_mfma_f32_16x16x32_bf16 v[118:121], v[160:163], v[184:187], v[118:121]
	v_mfma_f32_16x16x32_bf16 v[114:117], v[168:171], v[184:187], v[114:117]
	v_mfma_f32_16x16x32_bf16 v[102:105], v[160:163], v[192:195], v[102:105]
	v_mfma_f32_16x16x32_bf16 v[98:101], v[168:171], v[192:195], v[98:101]
	v_mfma_f32_16x16x32_bf16 v[86:89], v[160:163], v[200:203], v[86:89]
	v_mfma_f32_16x16x32_bf16 v[82:85], v[168:171], v[200:203], v[82:85]
	s_setprio 0
	s_barrier
	s_add_i32 s46, s37, s13
	v_lshl_add_u64 v[220:221], s[26:27], 0, v[134:135]
	s_mov_b32 m0, s46
	ds_read_b128 v[204:207], v151
	ds_read_b128 v[208:211], v151 offset:1024
	ds_read_b128 v[212:215], v151 offset:2048
	ds_read_b128 v[216:219], v151 offset:3072
	global_load_lds_dwordx4 v[220:221], off
	v_lshl_add_u64 v[222:223], s[26:27], 0, v[130:131]
	s_add_i32 m0, s46, 0x2000
	s_nop 0
	global_load_lds_dwordx4 v[222:223], off
	s_barrier
	s_waitcnt lgkmcnt(0)
	s_setprio 1
	s_waitcnt lgkmcnt(0)
	v_mfma_f32_16x16x32_bf16 v[110:113], v[204:207], v[172:175], v[110:113]
	v_mfma_f32_16x16x32_bf16 v[106:109], v[212:215], v[172:175], v[106:109]
	v_mfma_f32_16x16x32_bf16 v[94:97], v[204:207], v[180:183], v[94:97]
	v_mfma_f32_16x16x32_bf16 v[90:93], v[212:215], v[180:183], v[90:93]
	v_mfma_f32_16x16x32_bf16 v[78:81], v[204:207], v[188:191], v[78:81]
	v_mfma_f32_16x16x32_bf16 v[74:77], v[212:215], v[188:191], v[74:77]
	v_mfma_f32_16x16x32_bf16 v[70:73], v[204:207], v[196:199], v[70:73]
	v_mfma_f32_16x16x32_bf16 v[66:69], v[212:215], v[196:199], v[66:69]
	v_mfma_f32_16x16x32_bf16 v[110:113], v[208:211], v[176:179], v[110:113]
	v_mfma_f32_16x16x32_bf16 v[106:109], v[216:219], v[176:179], v[106:109]
	v_mfma_f32_16x16x32_bf16 v[94:97], v[208:211], v[184:187], v[94:97]
	v_mfma_f32_16x16x32_bf16 v[90:93], v[216:219], v[184:187], v[90:93]
	v_mfma_f32_16x16x32_bf16 v[78:81], v[208:211], v[192:195], v[78:81]
	v_mfma_f32_16x16x32_bf16 v[74:77], v[216:219], v[192:195], v[74:77]
	v_mfma_f32_16x16x32_bf16 v[70:73], v[208:211], v[200:203], v[70:73]
	v_mfma_f32_16x16x32_bf16 v[66:69], v[216:219], v[200:203], v[66:69]
	s_setprio 0
	s_mov_b32 m0, s9
	v_lshl_add_u64 v[224:225], s[28:29], 0, v[136:137]
	s_barrier
	ds_read_b128 v[172:175], v150 offset:16384
	ds_read_b128 v[176:179], v150 offset:17408
	ds_read_b128 v[180:183], v150 offset:18432
	ds_read_b128 v[184:187], v150 offset:19456
	ds_read_b128 v[188:191], v150 offset:20480
	ds_read_b128 v[192:195], v150 offset:21504
	ds_read_b128 v[196:199], v150 offset:22528
	ds_read_b128 v[200:203], v150 offset:23552
	global_load_lds_dwordx4 v[224:225], off
	v_lshl_add_u64 v[226:227], s[28:29], 0, v[132:133]
	s_mov_b32 m0, s30
	s_nop 0
	global_load_lds_dwordx4 v[226:227], off
	s_barrier
	s_waitcnt lgkmcnt(0)
	s_setprio 1
	s_waitcnt lgkmcnt(0)
	v_mfma_f32_16x16x32_bf16 v[62:65], v[156:159], v[172:175], v[62:65]
	v_mfma_f32_16x16x32_bf16 v[58:61], v[164:167], v[172:175], v[58:61]
	v_mfma_f32_16x16x32_bf16 v[54:57], v[156:159], v[180:183], v[54:57]
	v_mfma_f32_16x16x32_bf16 v[50:53], v[164:167], v[180:183], v[50:53]
	v_mfma_f32_16x16x32_bf16 v[38:41], v[156:159], v[188:191], v[38:41]
	v_mfma_f32_16x16x32_bf16 v[34:37], v[164:167], v[188:191], v[34:37]
	v_mfma_f32_16x16x32_bf16 v[22:25], v[156:159], v[196:199], v[22:25]
	v_mfma_f32_16x16x32_bf16 v[18:21], v[164:167], v[196:199], v[18:21]
	v_mfma_f32_16x16x32_bf16 v[62:65], v[160:163], v[176:179], v[62:65]
	v_mfma_f32_16x16x32_bf16 v[58:61], v[168:171], v[176:179], v[58:61]
	v_mfma_f32_16x16x32_bf16 v[54:57], v[160:163], v[184:187], v[54:57]
	v_mfma_f32_16x16x32_bf16 v[50:53], v[168:171], v[184:187], v[50:53]
	v_mfma_f32_16x16x32_bf16 v[38:41], v[160:163], v[192:195], v[38:41]
	v_mfma_f32_16x16x32_bf16 v[34:37], v[168:171], v[192:195], v[34:37]
	v_mfma_f32_16x16x32_bf16 v[22:25], v[160:163], v[200:203], v[22:25]
	v_mfma_f32_16x16x32_bf16 v[18:21], v[168:171], v[200:203], v[18:21]
	s_setprio 0
	s_barrier
; #define PG8_STAGE(bufoff, gbase, voff) do { _Pragma("unroll") for (int _i = 0; _i < 2; ++_i) \
;         __builtin_amdgcn_global_load_lds((const unsigned*)((const char*)(gbase) + (voff)[_i]), (LAS unsigned*)(lds + (bufoff) + ldsw + _i * 8192), 16, 0, 0); } while (0)
; #define PG8_LDA(dst, b, h) do { _Pragma("unroll") for (int m = 0; m < 4; ++m) _Pragma("unroll") for (int k = 0; k < 2; ++k) dst[m][k] = *(const LAS bf16x8*)(lds + PG8_SA(b, h) + aoff + m * 2048 + k * 1024); } while (0)
; #define PG8_LDB(dst, b, h) do { _Pragma("unroll") for (int n = 0; n < 2; ++n) _Pragma("unroll") for (int k = 0; k < 2; ++k) dst[n][k] = *(const LAS bf16x8*)(lds + PG8_SB(b, h) + boff + n * 2048 + k * 1024); } while (0)
; #define PG8_MMA(ai, bj, At, Bt) do { __builtin_amdgcn_s_setprio(1); _Pragma("unroll") for (int m = 0; m < 4; ++m) _Pragma("unroll") for (int n = 0; n < 2; ++n) _Pragma("unroll") for (int k = 0; k < 2; ++k) \
;         acc[ai][bj][m][n] = __builtin_amdgcn_mfma_f32_16x16x32_bf16(Bt[n][k], At[m][k], acc[ai][bj][m][n], 0, 0, 0); __builtin_amdgcn_s_setprio(0); } while (0)
; #define PG8_WAIT_V(n) asm volatile("s_waitcnt vmcnt(" #n ")" ::: "memory")
; #define PG8_WAIT_L(n) asm volatile("s_waitcnt lgkmcnt(" #n ")" ::: "memory")
; #define PG8_BAR __builtin_amdgcn_s_barrier()
; #define PG8_SCHED __builtin_amdgcn_sched_barrier(0)
; template <class Epi, class Sched>
; DI void gemm_phase(LAS unsigned char* lds, const Gemm g, const Sched& S, const Epi& E) {
;     ...
;             PG8_STAGE(PG8_SB(0, 1), b2 + hstep, voffB);
;             PG8_WAIT_V(6); PG8_BAR; PG8_MMA(1, 1, At, B1); PG8_BAR;
;             PG8_LDB(B0, 1, 0); PG8_SCHED; PG8_LDA(At, 1, 0); PG8_STAGE(PG8_SA(0, 1), a2 + hstep, voffA);
;             PG8_WAIT_L(8); PG8_BAR; PG8_WAIT_L(0); PG8_MMA(0, 0, At, B0); PG8_BAR; PG8_SCHED;
;             PG8_LDB(B1, 1, 1); PG8_STAGE(PG8_SB(1, 0), b3, voffB);
;             PG8_BAR; PG8_WAIT_L(0); PG8_MMA(0, 1, At, B1); PG8_BAR;
;             PG8_LDA(At, 1, 1); PG8_STAGE(PG8_SA(1, 0), a3, voffA);
;             PG8_BAR; PG8_WAIT_L(0); PG8_MMA(1, 0, At, B0); PG8_BAR; PG8_SCHED;
	s_add_u32 s46, s26, 0x10000
	s_addc_u32 s47, s27, 0
	s_add_i32 s48, s38, s13
	v_lshl_add_u64 v[156:157], s[46:47], 0, v[134:135]
	s_mov_b32 m0, s48
	s_nop 0
	global_load_lds_dwordx4 v[156:157], off
	v_lshl_add_u64 v[156:157], s[46:47], 0, v[130:131]
	s_add_i32 m0, s48, 0x2000
	s_nop 0
	global_load_lds_dwordx4 v[156:157], off
	s_waitcnt vmcnt(6)
	s_barrier
	s_setprio 1
	v_mfma_f32_16x16x32_bf16 v[46:49], v[204:207], v[172:175], v[46:49]
	v_mfma_f32_16x16x32_bf16 v[42:45], v[212:215], v[172:175], v[42:45]
	v_mfma_f32_16x16x32_bf16 v[30:33], v[204:207], v[180:183], v[30:33]
	v_mfma_f32_16x16x32_bf16 v[26:29], v[212:215], v[180:183], v[26:29]
	v_mfma_f32_16x16x32_bf16 v[14:17], v[204:207], v[188:191], v[14:17]
	v_mfma_f32_16x16x32_bf16 v[10:13], v[212:215], v[188:191], v[10:13]
	v_mfma_f32_16x16x32_bf16 v[6:9], v[204:207], v[196:199], v[6:9]
	v_mfma_f32_16x16x32_bf16 v[2:5], v[212:215], v[196:199], v[2:5]
	v_mfma_f32_16x16x32_bf16 v[46:49], v[208:211], v[176:179], v[46:49]
	v_mfma_f32_16x16x32_bf16 v[42:45], v[216:219], v[176:179], v[42:45]
	v_mfma_f32_16x16x32_bf16 v[30:33], v[208:211], v[184:187], v[30:33]
	v_mfma_f32_16x16x32_bf16 v[26:29], v[216:219], v[184:187], v[26:29]
	v_mfma_f32_16x16x32_bf16 v[14:17], v[208:211], v[192:195], v[14:17]
	v_mfma_f32_16x16x32_bf16 v[10:13], v[216:219], v[192:195], v[10:13]
	v_mfma_f32_16x16x32_bf16 v[6:9], v[208:211], v[200:203], v[6:9]
	v_mfma_f32_16x16x32_bf16 v[2:5], v[216:219], v[200:203], v[2:5]
	s_setprio 0
	s_add_i32 s46, 0, 0x18000
	v_add_u32_e32 v154, s46, v147
	s_barrier
	ds_read_b128 v[156:159], v154
	ds_read_b128 v[160:163], v154 offset:1024
	ds_read_b128 v[164:167], v154 offset:2048
	ds_read_b128 v[168:171], v154 offset:3072
	s_add_u32 s28, s28, 0x40000
	s_addc_u32 s29, s29, 0
	s_mov_b32 m0, s31
	v_lshl_add_u64 v[204:205], s[28:29], 0, v[136:137]
	ds_read_b128 v[172:175], v150 offset:32768
	ds_read_b128 v[176:179], v150 offset:33792
	ds_read_b128 v[180:183], v150 offset:34816
	ds_read_b128 v[184:187], v150 offset:35840
	ds_read_b128 v[188:191], v150 offset:36864
	ds_read_b128 v[192:195], v150 offset:37888
	ds_read_b128 v[196:199], v150 offset:38912
	ds_read_b128 v[200:203], v150 offset:39936
	global_load_lds_dwordx4 v[204:205], off
	v_lshl_add_u64 v[204:205], s[28:29], 0, v[132:133]
	s_mov_b32 m0, s33
	s_nop 0
	global_load_lds_dwordx4 v[204:205], off
	s_waitcnt lgkmcnt(8)
	s_barrier
	s_waitcnt lgkmcnt(0)
	s_setprio 1
	s_waitcnt lgkmcnt(0)
	v_mfma_f32_16x16x32_bf16 v[126:129], v[156:159], v[172:175], v[126:129]
	v_mfma_f32_16x16x32_bf16 v[122:125], v[164:167], v[172:175], v[122:125]
	v_mfma_f32_16x16x32_bf16 v[118:121], v[156:159], v[180:183], v[118:121]
	v_mfma_f32_16x16x32_bf16 v[114:117], v[164:167], v[180:183], v[114:117]
	v_mfma_f32_16x16x32_bf16 v[102:105], v[156:159], v[188:191], v[102:105]
	v_mfma_f32_16x16x32_bf16 v[98:101], v[164:167], v[188:191], v[98:101]
	v_mfma_f32_16x16x32_bf16 v[86:89], v[156:159], v[196:199], v[86:89]
	v_mfma_f32_16x16x32_bf16 v[82:85], v[164:167], v[196:199], v[82:85]
	v_mfma_f32_16x16x32_bf16 v[126:129], v[160:163], v[176:179], v[126:129]
	v_mfma_f32_16x16x32_bf16 v[122:125], v[168:171], v[176:179], v[122:125]
	v_mfma_f32_16x16x32_bf16 v[118:121], v[160:163], v[184:187], v[118:121]
	v_mfma_f32_16x16x32_bf16 v[114:117], v[168:171], v[184:187], v[114:117]
	v_mfma_f32_16x16x32_bf16 v[102:105], v[160:163], v[192:195], v[102:105]
	v_mfma_f32_16x16x32_bf16 v[98:101], v[168:171], v[192:195], v[98:101]
	v_mfma_f32_16x16x32_bf16 v[86:89], v[160:163], v[200:203], v[86:89]
	v_mfma_f32_16x16x32_bf16 v[82:85], v[168:171], v[200:203], v[82:85]
	s_setprio 0
	s_barrier
	s_add_i32 s28, 0, 0x1c000
	s_add_i32 s29, s46, s13
	v_add_u32_e32 v154, s28, v147
	v_lshl_add_u64 v[220:221], v[220:221], 0, s[6:7]
	s_mov_b32 m0, s29
	ds_read_b128 v[204:207], v154
	ds_read_b128 v[208:211], v154 offset:1024
	ds_read_b128 v[212:215], v154 offset:2048
	ds_read_b128 v[216:219], v154 offset:3072
	global_load_lds_dwordx4 v[220:221], off
	v_lshl_add_u64 v[220:221], v[222:223], 0, s[6:7]
	s_add_i32 m0, s29, 0x2000
	s_nop 0
	global_load_lds_dwordx4 v[220:221], off
	s_barrier
	s_waitcnt lgkmcnt(0)
	s_setprio 1
	s_waitcnt lgkmcnt(0)
	v_mfma_f32_16x16x32_bf16 v[110:113], v[204:207], v[172:175], v[110:113]
	v_mfma_f32_16x16x32_bf16 v[106:109], v[212:215], v[172:175], v[106:109]
	v_mfma_f32_16x16x32_bf16 v[94:97], v[204:207], v[180:183], v[94:97]
	v_mfma_f32_16x16x32_bf16 v[90:93], v[212:215], v[180:183], v[90:93]
	v_mfma_f32_16x16x32_bf16 v[78:81], v[204:207], v[188:191], v[78:81]
	v_mfma_f32_16x16x32_bf16 v[74:77], v[212:215], v[188:191], v[74:77]
	v_mfma_f32_16x16x32_bf16 v[70:73], v[204:207], v[196:199], v[70:73]
	v_mfma_f32_16x16x32_bf16 v[66:69], v[212:215], v[196:199], v[66:69]
	v_mfma_f32_16x16x32_bf16 v[110:113], v[208:211], v[176:179], v[110:113]
	v_mfma_f32_16x16x32_bf16 v[106:109], v[216:219], v[176:179], v[106:109]
	v_mfma_f32_16x16x32_bf16 v[94:97], v[208:211], v[184:187], v[94:97]
	v_mfma_f32_16x16x32_bf16 v[90:93], v[216:219], v[184:187], v[90:93]
	v_mfma_f32_16x16x32_bf16 v[78:81], v[208:211], v[192:195], v[78:81]
	v_mfma_f32_16x16x32_bf16 v[74:77], v[216:219], v[192:195], v[74:77]
	v_mfma_f32_16x16x32_bf16 v[70:73], v[208:211], v[200:203], v[70:73]
	v_mfma_f32_16x16x32_bf16 v[66:69], v[216:219], v[200:203], v[66:69]
	s_setprio 0
	s_mov_b32 m0, s35
	v_lshl_add_u64 v[220:221], v[224:225], 0, s[6:7]
	s_barrier
	ds_read_b128 v[172:175], v150 offset:49152
	ds_read_b128 v[176:179], v150 offset:50176
	ds_read_b128 v[180:183], v150 offset:51200
	ds_read_b128 v[184:187], v150 offset:52224
	ds_read_b128 v[188:191], v150 offset:53248
	ds_read_b128 v[192:195], v150 offset:54272
	ds_read_b128 v[196:199], v150 offset:55296
	ds_read_b128 v[200:203], v150 offset:56320
	global_load_lds_dwordx4 v[220:221], off
	v_lshl_add_u64 v[220:221], v[226:227], 0, s[6:7]
	s_mov_b32 m0, s36
	s_nop 0
	global_load_lds_dwordx4 v[220:221], off
	s_barrier
; DI unsigned pk_bf16(float a, float b) { f32x2 v = {a, b}; bf2_t r = __builtin_convertvector(v, bf2_t); return __builtin_bit_cast(unsigned, r); }
; #define PG8_STAGE(bufoff, gbase, voff) do { _Pragma("unroll") for (int _i = 0; _i < 2; ++_i) \
;         __builtin_amdgcn_global_load_lds((const unsigned*)((const char*)(gbase) + (voff)[_i]), (LAS unsigned*)(lds + (bufoff) + ldsw + _i * 8192), 16, 0, 0); } while (0)
; #define PG8_MMA(ai, bj, At, Bt) do { __builtin_amdgcn_s_setprio(1); _Pragma("unroll") for (int m = 0; m < 4; ++m) _Pragma("unroll") for (int n = 0; n < 2; ++n) _Pragma("unroll") for (int k = 0; k < 2; ++k) \
;         acc[ai][bj][m][n] = __builtin_amdgcn_mfma_f32_16x16x32_bf16(Bt[n][k], At[m][k], acc[ai][bj][m][n], 0, 0, 0); __builtin_amdgcn_s_setprio(0); } while (0)
; #define PG8_WAIT_V(n) asm volatile("s_waitcnt vmcnt(" #n ")" ::: "memory")
; #define PG8_BAR __builtin_amdgcn_s_barrier()
;     DI void operator()(const f32x4 (&acc)[2][2][4][2], const Unit& u, int wr, int wc, int fr, int fq) const {
;         const int row0 = u.pm * BM + wr * 64 + fr, col0 = u.pn * BM + wc * 32 + 8 * fq;
; #pragma unroll
;         for (int ai = 0; ai < 2; ++ai)
; #pragma unroll
;             for (int m = 0; m < 4; ++m) { bf16_t* rowp = O + (size_t)(row0 + ai * HALF + m * 16) * ldc + col0;
; #pragma unroll
;                 for (int bj = 0; bj < 2; ++bj) { const f32x4 v0 = acc[ai][bj][m][0], v1 = acc[ai][bj][m][1];
;                     u32x4 w; w.x = pk_bf16(v0[0], v0[1]); w.y = pk_bf16(v0[2], v0[3]); w.z = pk_bf16(v1[0], v1[1]); w.w = pk_bf16(v1[2], v1[3]);
;                     *(u32x4*)(rowp + bj * HALF) = w; } }
; template <class Epi, class Sched>
; DI void gemm_phase(LAS unsigned char* lds, const Gemm g, const Sched& S, const Epi& E) {
;     ...
;             PG8_STAGE(PG8_SB(1, 1), b3 + hstep, voffB);
;             PG8_WAIT_V(6); PG8_BAR; PG8_MMA(1, 1, At, B1); PG8_BAR;
;         }
	s_waitcnt lgkmcnt(0)
	s_setprio 1
	s_waitcnt lgkmcnt(0)
	v_mfma_f32_16x16x32_bf16 v[62:65], v[156:159], v[172:175], v[62:65]
	v_mfma_f32_16x16x32_bf16 v[58:61], v[164:167], v[172:175], v[58:61]
	v_mfma_f32_16x16x32_bf16 v[54:57], v[156:159], v[180:183], v[54:57]
	v_mfma_f32_16x16x32_bf16 v[50:53], v[164:167], v[180:183], v[50:53]
	v_mfma_f32_16x16x32_bf16 v[38:41], v[156:159], v[188:191], v[38:41]
	v_mfma_f32_16x16x32_bf16 v[34:37], v[164:167], v[188:191], v[34:37]
	v_mfma_f32_16x16x32_bf16 v[22:25], v[156:159], v[196:199], v[22:25]
	v_mfma_f32_16x16x32_bf16 v[18:21], v[164:167], v[196:199], v[18:21]
	v_mfma_f32_16x16x32_bf16 v[62:65], v[160:163], v[176:179], v[62:65]
	v_mfma_f32_16x16x32_bf16 v[58:61], v[168:171], v[176:179], v[58:61]
	v_mfma_f32_16x16x32_bf16 v[54:57], v[160:163], v[184:187], v[54:57]
	v_mfma_f32_16x16x32_bf16 v[50:53], v[168:171], v[184:187], v[50:53]
	v_mfma_f32_16x16x32_bf16 v[38:41], v[160:163], v[192:195], v[38:41]
	v_mfma_f32_16x16x32_bf16 v[34:37], v[168:171], v[192:195], v[34:37]
	v_mfma_f32_16x16x32_bf16 v[22:25], v[160:163], v[200:203], v[22:25]
	v_mfma_f32_16x16x32_bf16 v[18:21], v[168:171], v[200:203], v[18:21]
	s_setprio 0
	s_barrier
	s_add_u32 s26, s26, 0x10080
	s_addc_u32 s27, s27, 0
	s_add_i32 s28, s28, s13
	v_lshl_add_u64 v[156:157], s[26:27], 0, v[134:135]
	s_mov_b32 m0, s28
	s_nop 0
	global_load_lds_dwordx4 v[156:157], off
	v_lshl_add_u64 v[156:157], s[26:27], 0, v[130:131]
	s_add_i32 m0, s28, 0x2000
	s_nop 0
	global_load_lds_dwordx4 v[156:157], off
	s_waitcnt vmcnt(6)
	s_barrier
	s_setprio 1
	v_mfma_f32_16x16x32_bf16 v[46:49], v[204:207], v[172:175], v[46:49]
	v_mfma_f32_16x16x32_bf16 v[42:45], v[212:215], v[172:175], v[42:45]
	v_mfma_f32_16x16x32_bf16 v[30:33], v[204:207], v[180:183], v[30:33]
	v_mfma_f32_16x16x32_bf16 v[26:29], v[212:215], v[180:183], v[26:29]
	v_mfma_f32_16x16x32_bf16 v[14:17], v[204:207], v[188:191], v[14:17]
	v_mfma_f32_16x16x32_bf16 v[10:13], v[212:215], v[188:191], v[10:13]
	v_mfma_f32_16x16x32_bf16 v[6:9], v[204:207], v[196:199], v[6:9]
	v_mfma_f32_16x16x32_bf16 v[2:5], v[212:215], v[196:199], v[2:5]
	v_mfma_f32_16x16x32_bf16 v[46:49], v[208:211], v[176:179], v[46:49]
	v_mfma_f32_16x16x32_bf16 v[42:45], v[216:219], v[176:179], v[42:45]
	v_mfma_f32_16x16x32_bf16 v[30:33], v[208:211], v[184:187], v[30:33]
	v_mfma_f32_16x16x32_bf16 v[26:29], v[216:219], v[184:187], v[26:29]
	v_mfma_f32_16x16x32_bf16 v[14:17], v[208:211], v[192:195], v[14:17]
	v_mfma_f32_16x16x32_bf16 v[10:13], v[216:219], v[192:195], v[10:13]
	v_mfma_f32_16x16x32_bf16 v[6:9], v[208:211], v[200:203], v[6:9]
	v_mfma_f32_16x16x32_bf16 v[2:5], v[216:219], v[200:203], v[2:5]
	s_setprio 0
	s_add_i32 s45, s45, 2
	s_add_u32 s24, s24, 0x100
	s_addc_u32 s25, s25, 0
	s_add_u32 s43, s43, 0x100
	s_addc_u32 s44, s44, 0
	s_cmp_gt_u32 s45, 13
	s_barrier
	s_cbranch_scc0 .LBB0_130
	v_and_b32_e32 v156, 63, v1
	v_lshrrev_b32_e32 v240, 3, v156
	v_and_b32_e32 v157, 0xffffffc0, v146
	v_add_u32_e32 v157, v157, v240
	v_lshl_add_u32 v157, s8, 8, v157
	v_mul_u32_u24_e32 v157, 0x2200, v157
	v_and_b32_e32 v241, 0xffffffc0, v148
	v_lshl_or_b32 v241, s40, 8, v241
	v_and_b32_e32 v242, 7, v156
	v_lshlrev_b32_e32 v242, 4, v242
	v_lshl_add_u32 v244, v241, 1, v157
	v_add_u32_e32 v244, v244, v242
	v_and_b32_e32 v243, 3, v156
	v_lshlrev_b32_e32 v243, 4, v243
	v_bfe_u32 v242, v156, 2, 1
	v_lshl_or_b32 v243, v242, 3, v243
	v_or_b32_e32 v243, v243, v240
	v_lshlrev_b32_e32 v154, 2, v243
	v_add_u32_e32 v245, 0x11000, v244
	v_add_u32_e32 v246, 0x22000, v244
	v_add_u32_e32 v247, 0x33000, v244
	v_add_u32_e32 v248, 0x44000, v244
	v_add_u32_e32 v249, 0x55000, v244
	v_add_u32_e32 v250, 0x66000, v244
	v_add_u32_e32 v251, 0x77000, v244
	v_add_u32_e32 v252, 0x110000, v244
	v_add_u32_e32 v253, 0x121000, v244
	v_add_u32_e32 v254, 0x132000, v244
	v_add_u32_e32 v255, 0x143000, v244
	v_add_u32_e32 v158, 0x154000, v244
	v_add_u32_e32 v159, 0x165000, v244
	v_add_u32_e32 v160, 0x176000, v244
	v_add_u32_e32 v161, 0x187000, v244
	s_and_b64 vcc, exec, s[0:1]
	s_mov_b32 s40, s10
	s_mov_b32 s8, s18
	s_mov_b64 s[26:27], s[22:23]
	s_mov_b64 s[24:25], s[20:21]
	v_cvt_pk_bf16_f32 v126, v126, v127
	v_cvt_pk_bf16_f32 v127, v128, v129
	v_cvt_pk_bf16_f32 v128, v122, v123
	v_cvt_pk_bf16_f32 v129, v124, v125
	v_cvt_pk_bf16_f32 v110, v110, v111
	v_cvt_pk_bf16_f32 v111, v112, v113
	v_cvt_pk_bf16_f32 v112, v106, v107
	v_cvt_pk_bf16_f32 v113, v108, v109
	v_mov_b32_dpp v240, v126 row_ror:8 row_mask:0xf bank_mask:0xf
	v_mov_b32_dpp v241, v127 row_ror:8 row_mask:0xf bank_mask:0xf
	v_mov_b32_dpp v242, v128 row_ror:8 row_mask:0xf bank_mask:0xf
	v_mov_b32_dpp v243, v129 row_ror:8 row_mask:0xf bank_mask:0xf
	v_mov_b32_dpp v126, v110 row_ror:8 row_mask:0xf bank_mask:0xc
	v_mov_b32_dpp v127, v111 row_ror:8 row_mask:0xf bank_mask:0xc
	v_mov_b32_dpp v128, v112 row_ror:8 row_mask:0xf bank_mask:0xc
	v_mov_b32_dpp v129, v113 row_ror:8 row_mask:0xf bank_mask:0xc
	v_mov_b32_dpp v110, v240 quad_perm:[0,1,2,3] row_mask:0xf bank_mask:0x3
	v_mov_b32_dpp v111, v241 quad_perm:[0,1,2,3] row_mask:0xf bank_mask:0x3
	v_mov_b32_dpp v112, v242 quad_perm:[0,1,2,3] row_mask:0xf bank_mask:0x3
	v_mov_b32_dpp v113, v243 quad_perm:[0,1,2,3] row_mask:0xf bank_mask:0x3
	ds_bpermute_b32 v122, v154, v126
	ds_bpermute_b32 v123, v154, v127
	ds_bpermute_b32 v124, v154, v128
	ds_bpermute_b32 v125, v154, v129
	ds_bpermute_b32 v106, v154, v110
	ds_bpermute_b32 v107, v154, v111
	ds_bpermute_b32 v108, v154, v112
	ds_bpermute_b32 v109, v154, v113
	v_cvt_pk_bf16_f32 v118, v118, v119
	v_cvt_pk_bf16_f32 v119, v120, v121
	v_cvt_pk_bf16_f32 v120, v114, v115
	v_cvt_pk_bf16_f32 v121, v116, v117
	v_cvt_pk_bf16_f32 v94, v94, v95
	v_cvt_pk_bf16_f32 v95, v96, v97
	v_cvt_pk_bf16_f32 v96, v90, v91
	v_cvt_pk_bf16_f32 v97, v92, v93
	v_mov_b32_dpp v240, v118 row_ror:8 row_mask:0xf bank_mask:0xf
	v_mov_b32_dpp v241, v119 row_ror:8 row_mask:0xf bank_mask:0xf
	v_mov_b32_dpp v242, v120 row_ror:8 row_mask:0xf bank_mask:0xf
	v_mov_b32_dpp v243, v121 row_ror:8 row_mask:0xf bank_mask:0xf
	v_mov_b32_dpp v118, v94 row_ror:8 row_mask:0xf bank_mask:0xc
	v_mov_b32_dpp v119, v95 row_ror:8 row_mask:0xf bank_mask:0xc
	v_mov_b32_dpp v120, v96 row_ror:8 row_mask:0xf bank_mask:0xc
	v_mov_b32_dpp v121, v97 row_ror:8 row_mask:0xf bank_mask:0xc
	v_mov_b32_dpp v94, v240 quad_perm:[0,1,2,3] row_mask:0xf bank_mask:0x3
	v_mov_b32_dpp v95, v241 quad_perm:[0,1,2,3] row_mask:0xf bank_mask:0x3
	v_mov_b32_dpp v96, v242 quad_perm:[0,1,2,3] row_mask:0xf bank_mask:0x3
	v_mov_b32_dpp v97, v243 quad_perm:[0,1,2,3] row_mask:0xf bank_mask:0x3
	s_waitcnt lgkmcnt(0)
; DI unsigned pk_bf16(float a, float b) { f32x2 v = {a, b}; bf2_t r = __builtin_convertvector(v, bf2_t); return __builtin_bit_cast(unsigned, r); }
;     DI void operator()(const f32x4 (&acc)[2][2][4][2], const Unit& u, int wr, int wc, int fr, int fq) const {
;     ...
;             for (int m = 0; m < 4; ++m) { bf16_t* rowp = O + (size_t)(row0 + ai * HALF + m * 16) * ldc + col0;
; #pragma unroll
;                 for (int bj = 0; bj < 2; ++bj) { const f32x4 v0 = acc[ai][bj][m][0], v1 = acc[ai][bj][m][1];
;                     u32x4 w; w.x = pk_bf16(v0[0], v0[1]); w.y = pk_bf16(v0[2], v0[3]); w.z = pk_bf16(v1[0], v1[1]); w.w = pk_bf16(v1[2], v1[3]);
;                     *(u32x4*)(rowp + bj * HALF) = w; } }
	global_store_dwordx4 v244, v[122:125], s[86:87] nt
	global_store_dwordx4 v245, v[106:109], s[86:87] nt
	ds_bpermute_b32 v114, v154, v118
	ds_bpermute_b32 v115, v154, v119
	ds_bpermute_b32 v116, v154, v120
	ds_bpermute_b32 v117, v154, v121
	ds_bpermute_b32 v90, v154, v94
	ds_bpermute_b32 v91, v154, v95
	ds_bpermute_b32 v92, v154, v96
	ds_bpermute_b32 v93, v154, v97
	v_cvt_pk_bf16_f32 v102, v102, v103
	v_cvt_pk_bf16_f32 v103, v104, v105
	v_cvt_pk_bf16_f32 v104, v98, v99
	v_cvt_pk_bf16_f32 v105, v100, v101
	v_cvt_pk_bf16_f32 v78, v78, v79
	v_cvt_pk_bf16_f32 v79, v80, v81
	v_cvt_pk_bf16_f32 v80, v74, v75
	v_cvt_pk_bf16_f32 v81, v76, v77
	v_mov_b32_dpp v240, v102 row_ror:8 row_mask:0xf bank_mask:0xf
	v_mov_b32_dpp v241, v103 row_ror:8 row_mask:0xf bank_mask:0xf
	v_mov_b32_dpp v242, v104 row_ror:8 row_mask:0xf bank_mask:0xf
	v_mov_b32_dpp v243, v105 row_ror:8 row_mask:0xf bank_mask:0xf
	v_mov_b32_dpp v102, v78 row_ror:8 row_mask:0xf bank_mask:0xc
	v_mov_b32_dpp v103, v79 row_ror:8 row_mask:0xf bank_mask:0xc
	v_mov_b32_dpp v104, v80 row_ror:8 row_mask:0xf bank_mask:0xc
	v_mov_b32_dpp v105, v81 row_ror:8 row_mask:0xf bank_mask:0xc
	v_mov_b32_dpp v78, v240 quad_perm:[0,1,2,3] row_mask:0xf bank_mask:0x3
	v_mov_b32_dpp v79, v241 quad_perm:[0,1,2,3] row_mask:0xf bank_mask:0x3
	v_mov_b32_dpp v80, v242 quad_perm:[0,1,2,3] row_mask:0xf bank_mask:0x3
	v_mov_b32_dpp v81, v243 quad_perm:[0,1,2,3] row_mask:0xf bank_mask:0x3
	s_waitcnt lgkmcnt(0)
	global_store_dwordx4 v246, v[114:117], s[86:87] nt
	global_store_dwordx4 v247, v[90:93], s[86:87] nt
	ds_bpermute_b32 v98, v154, v102
	ds_bpermute_b32 v99, v154, v103
	ds_bpermute_b32 v100, v154, v104
	ds_bpermute_b32 v101, v154, v105
	ds_bpermute_b32 v74, v154, v78
	ds_bpermute_b32 v75, v154, v79
	ds_bpermute_b32 v76, v154, v80
	ds_bpermute_b32 v77, v154, v81
	v_cvt_pk_bf16_f32 v86, v86, v87
	v_cvt_pk_bf16_f32 v87, v88, v89
	v_cvt_pk_bf16_f32 v88, v82, v83
	v_cvt_pk_bf16_f32 v89, v84, v85
	v_cvt_pk_bf16_f32 v70, v70, v71
	v_cvt_pk_bf16_f32 v71, v72, v73
	v_cvt_pk_bf16_f32 v72, v66, v67
	v_cvt_pk_bf16_f32 v73, v68, v69
	v_mov_b32_dpp v240, v86 row_ror:8 row_mask:0xf bank_mask:0xf
	v_mov_b32_dpp v241, v87 row_ror:8 row_mask:0xf bank_mask:0xf
	v_mov_b32_dpp v242, v88 row_ror:8 row_mask:0xf bank_mask:0xf
	v_mov_b32_dpp v243, v89 row_ror:8 row_mask:0xf bank_mask:0xf
	v_mov_b32_dpp v86, v70 row_ror:8 row_mask:0xf bank_mask:0xc
	v_mov_b32_dpp v87, v71 row_ror:8 row_mask:0xf bank_mask:0xc
	v_mov_b32_dpp v88, v72 row_ror:8 row_mask:0xf bank_mask:0xc
	v_mov_b32_dpp v89, v73 row_ror:8 row_mask:0xf bank_mask:0xc
	v_mov_b32_dpp v70, v240 quad_perm:[0,1,2,3] row_mask:0xf bank_mask:0x3
	v_mov_b32_dpp v71, v241 quad_perm:[0,1,2,3] row_mask:0xf bank_mask:0x3
	v_mov_b32_dpp v72, v242 quad_perm:[0,1,2,3] row_mask:0xf bank_mask:0x3
	v_mov_b32_dpp v73, v243 quad_perm:[0,1,2,3] row_mask:0xf bank_mask:0x3
	s_waitcnt lgkmcnt(0)
	global_store_dwordx4 v248, v[98:101], s[86:87] nt
	global_store_dwordx4 v249, v[74:77], s[86:87] nt
	ds_bpermute_b32 v82, v154, v86
	ds_bpermute_b32 v83, v154, v87
	ds_bpermute_b32 v84, v154, v88
	ds_bpermute_b32 v85, v154, v89
	ds_bpermute_b32 v66, v154, v70
	ds_bpermute_b32 v67, v154, v71
	ds_bpermute_b32 v68, v154, v72
	ds_bpermute_b32 v69, v154, v73
	v_cvt_pk_bf16_f32 v62, v62, v63
	v_cvt_pk_bf16_f32 v63, v64, v65
	v_cvt_pk_bf16_f32 v64, v58, v59
	v_cvt_pk_bf16_f32 v65, v60, v61
	v_cvt_pk_bf16_f32 v46, v46, v47
	v_cvt_pk_bf16_f32 v47, v48, v49
	v_cvt_pk_bf16_f32 v48, v42, v43
	v_cvt_pk_bf16_f32 v49, v44, v45
	v_mov_b32_dpp v240, v62 row_ror:8 row_mask:0xf bank_mask:0xf
	v_mov_b32_dpp v241, v63 row_ror:8 row_mask:0xf bank_mask:0xf
	v_mov_b32_dpp v242, v64 row_ror:8 row_mask:0xf bank_mask:0xf
	v_mov_b32_dpp v243, v65 row_ror:8 row_mask:0xf bank_mask:0xf
	v_mov_b32_dpp v62, v46 row_ror:8 row_mask:0xf bank_mask:0xc
	v_mov_b32_dpp v63, v47 row_ror:8 row_mask:0xf bank_mask:0xc
	v_mov_b32_dpp v64, v48 row_ror:8 row_mask:0xf bank_mask:0xc
	v_mov_b32_dpp v65, v49 row_ror:8 row_mask:0xf bank_mask:0xc
	v_mov_b32_dpp v46, v240 quad_perm:[0,1,2,3] row_mask:0xf bank_mask:0x3
	v_mov_b32_dpp v47, v241 quad_perm:[0,1,2,3] row_mask:0xf bank_mask:0x3
	v_mov_b32_dpp v48, v242 quad_perm:[0,1,2,3] row_mask:0xf bank_mask:0x3
	v_mov_b32_dpp v49, v243 quad_perm:[0,1,2,3] row_mask:0xf bank_mask:0x3
	s_waitcnt lgkmcnt(0)
; DI unsigned pk_bf16(float a, float b) { f32x2 v = {a, b}; bf2_t r = __builtin_convertvector(v, bf2_t); return __builtin_bit_cast(unsigned, r); }
; #define PG8_WAIT_V(n) asm volatile("s_waitcnt vmcnt(" #n ")" ::: "memory")
; #define PG8_BAR __builtin_amdgcn_s_barrier()
;     DI void operator()(const f32x4 (&acc)[2][2][4][2], const Unit& u, int wr, int wc, int fr, int fq) const {
;     ...
;             for (int m = 0; m < 4; ++m) { bf16_t* rowp = O + (size_t)(row0 + ai * HALF + m * 16) * ldc + col0;
; #pragma unroll
;                 for (int bj = 0; bj < 2; ++bj) { const f32x4 v0 = acc[ai][bj][m][0], v1 = acc[ai][bj][m][1];
;                     u32x4 w; w.x = pk_bf16(v0[0], v0[1]); w.y = pk_bf16(v0[2], v0[3]); w.z = pk_bf16(v1[0], v1[1]); w.w = pk_bf16(v1[2], v1[3]);
;                     *(u32x4*)(rowp + bj * HALF) = w; } }
; template <class Epi, class Sched>
; DI void gemm_phase(LAS unsigned char* lds, const Gemm g, const Sched& S, const Epi& E) {
;     ...
;         if (!has_next) break;
; #pragma unroll
;         for (int a = 0; a < 2; ++a)
; #pragma unroll
;             for (int b = 0; b < 2; ++b)
; #pragma unroll
;                 for (int m = 0; m < 4; ++m)
; #pragma unroll
;                     for (int n = 0; n < 2; ++n) acc[a][b][m][n] = (f32x4){0.f, 0.f, 0.f, 0.f};
;         cur = nxt; cA = nA; cB = nB; ++ui;
;     }
;     PG8_WAIT_V(0);
;     if (wr == 0) PG8_BAR;
	global_store_dwordx4 v250, v[82:85], s[86:87] nt
	global_store_dwordx4 v251, v[66:69], s[86:87] nt
	ds_bpermute_b32 v58, v154, v62
	ds_bpermute_b32 v59, v154, v63
	ds_bpermute_b32 v60, v154, v64
	ds_bpermute_b32 v61, v154, v65
	ds_bpermute_b32 v42, v154, v46
	ds_bpermute_b32 v43, v154, v47
	ds_bpermute_b32 v44, v154, v48
	ds_bpermute_b32 v45, v154, v49
	v_cvt_pk_bf16_f32 v54, v54, v55
	v_cvt_pk_bf16_f32 v55, v56, v57
	v_cvt_pk_bf16_f32 v56, v50, v51
	v_cvt_pk_bf16_f32 v57, v52, v53
	v_cvt_pk_bf16_f32 v30, v30, v31
	v_cvt_pk_bf16_f32 v31, v32, v33
	v_cvt_pk_bf16_f32 v32, v26, v27
	v_cvt_pk_bf16_f32 v33, v28, v29
	v_mov_b32_dpp v240, v54 row_ror:8 row_mask:0xf bank_mask:0xf
	v_mov_b32_dpp v241, v55 row_ror:8 row_mask:0xf bank_mask:0xf
	v_mov_b32_dpp v242, v56 row_ror:8 row_mask:0xf bank_mask:0xf
	v_mov_b32_dpp v243, v57 row_ror:8 row_mask:0xf bank_mask:0xf
	v_mov_b32_dpp v54, v30 row_ror:8 row_mask:0xf bank_mask:0xc
	v_mov_b32_dpp v55, v31 row_ror:8 row_mask:0xf bank_mask:0xc
	v_mov_b32_dpp v56, v32 row_ror:8 row_mask:0xf bank_mask:0xc
	v_mov_b32_dpp v57, v33 row_ror:8 row_mask:0xf bank_mask:0xc
	v_mov_b32_dpp v30, v240 quad_perm:[0,1,2,3] row_mask:0xf bank_mask:0x3
	v_mov_b32_dpp v31, v241 quad_perm:[0,1,2,3] row_mask:0xf bank_mask:0x3
	v_mov_b32_dpp v32, v242 quad_perm:[0,1,2,3] row_mask:0xf bank_mask:0x3
	v_mov_b32_dpp v33, v243 quad_perm:[0,1,2,3] row_mask:0xf bank_mask:0x3
	s_waitcnt lgkmcnt(0)
	global_store_dwordx4 v252, v[58:61], s[86:87] nt
	global_store_dwordx4 v253, v[42:45], s[86:87] nt
	ds_bpermute_b32 v50, v154, v54
	ds_bpermute_b32 v51, v154, v55
	ds_bpermute_b32 v52, v154, v56
	ds_bpermute_b32 v53, v154, v57
	ds_bpermute_b32 v26, v154, v30
	ds_bpermute_b32 v27, v154, v31
	ds_bpermute_b32 v28, v154, v32
	ds_bpermute_b32 v29, v154, v33
	v_cvt_pk_bf16_f32 v38, v38, v39
	v_cvt_pk_bf16_f32 v39, v40, v41
	v_cvt_pk_bf16_f32 v40, v34, v35
	v_cvt_pk_bf16_f32 v41, v36, v37
	v_cvt_pk_bf16_f32 v14, v14, v15
	v_cvt_pk_bf16_f32 v15, v16, v17
	v_cvt_pk_bf16_f32 v16, v10, v11
	v_cvt_pk_bf16_f32 v17, v12, v13
	v_mov_b32_dpp v240, v38 row_ror:8 row_mask:0xf bank_mask:0xf
	v_mov_b32_dpp v241, v39 row_ror:8 row_mask:0xf bank_mask:0xf
	v_mov_b32_dpp v242, v40 row_ror:8 row_mask:0xf bank_mask:0xf
	v_mov_b32_dpp v243, v41 row_ror:8 row_mask:0xf bank_mask:0xf
	v_mov_b32_dpp v38, v14 row_ror:8 row_mask:0xf bank_mask:0xc
	v_mov_b32_dpp v39, v15 row_ror:8 row_mask:0xf bank_mask:0xc
	v_mov_b32_dpp v40, v16 row_ror:8 row_mask:0xf bank_mask:0xc
	v_mov_b32_dpp v41, v17 row_ror:8 row_mask:0xf bank_mask:0xc
	v_mov_b32_dpp v14, v240 quad_perm:[0,1,2,3] row_mask:0xf bank_mask:0x3
	v_mov_b32_dpp v15, v241 quad_perm:[0,1,2,3] row_mask:0xf bank_mask:0x3
	v_mov_b32_dpp v16, v242 quad_perm:[0,1,2,3] row_mask:0xf bank_mask:0x3
	v_mov_b32_dpp v17, v243 quad_perm:[0,1,2,3] row_mask:0xf bank_mask:0x3
	s_waitcnt lgkmcnt(0)
	global_store_dwordx4 v254, v[50:53], s[86:87] nt
	global_store_dwordx4 v255, v[26:29], s[86:87] nt
	ds_bpermute_b32 v34, v154, v38
	ds_bpermute_b32 v35, v154, v39
	ds_bpermute_b32 v36, v154, v40
	ds_bpermute_b32 v37, v154, v41
	ds_bpermute_b32 v10, v154, v14
	ds_bpermute_b32 v11, v154, v15
	ds_bpermute_b32 v12, v154, v16
	ds_bpermute_b32 v13, v154, v17
	v_cvt_pk_bf16_f32 v22, v22, v23
	v_cvt_pk_bf16_f32 v23, v24, v25
	v_cvt_pk_bf16_f32 v24, v18, v19
	v_cvt_pk_bf16_f32 v25, v20, v21
	v_cvt_pk_bf16_f32 v6, v6, v7
	v_cvt_pk_bf16_f32 v7, v8, v9
	v_cvt_pk_bf16_f32 v8, v2, v3
	v_cvt_pk_bf16_f32 v9, v4, v5
	v_mov_b32_dpp v240, v22 row_ror:8 row_mask:0xf bank_mask:0xf
	v_mov_b32_dpp v241, v23 row_ror:8 row_mask:0xf bank_mask:0xf
	v_mov_b32_dpp v242, v24 row_ror:8 row_mask:0xf bank_mask:0xf
	v_mov_b32_dpp v243, v25 row_ror:8 row_mask:0xf bank_mask:0xf
	v_mov_b32_dpp v22, v6 row_ror:8 row_mask:0xf bank_mask:0xc
	v_mov_b32_dpp v23, v7 row_ror:8 row_mask:0xf bank_mask:0xc
	v_mov_b32_dpp v24, v8 row_ror:8 row_mask:0xf bank_mask:0xc
	v_mov_b32_dpp v25, v9 row_ror:8 row_mask:0xf bank_mask:0xc
	v_mov_b32_dpp v6, v240 quad_perm:[0,1,2,3] row_mask:0xf bank_mask:0x3
	v_mov_b32_dpp v7, v241 quad_perm:[0,1,2,3] row_mask:0xf bank_mask:0x3
	v_mov_b32_dpp v8, v242 quad_perm:[0,1,2,3] row_mask:0xf bank_mask:0x3
	v_mov_b32_dpp v9, v243 quad_perm:[0,1,2,3] row_mask:0xf bank_mask:0x3
	s_waitcnt lgkmcnt(0)
	global_store_dwordx4 v158, v[34:37], s[86:87] nt
	global_store_dwordx4 v159, v[10:13], s[86:87] nt
	ds_bpermute_b32 v18, v154, v22
	ds_bpermute_b32 v19, v154, v23
	ds_bpermute_b32 v20, v154, v24
	ds_bpermute_b32 v21, v154, v25
	ds_bpermute_b32 v2, v154, v6
	ds_bpermute_b32 v3, v154, v7
	ds_bpermute_b32 v4, v154, v8
	ds_bpermute_b32 v5, v154, v9
	s_waitcnt lgkmcnt(0)
	global_store_dwordx4 v160, v[18:21], s[86:87] nt
	global_store_dwordx4 v161, v[2:5], s[86:87] nt
	s_cbranch_vccz .LBB0_123
	s_waitcnt vmcnt(0)
	s_cmpk_gt_u32 s12, 0xff
	s_cbranch_scc1 .LBB0_134
	s_barrier

; #define PG8_STAGE(bufoff, gbase, voff) do { _Pragma("unroll") for (int _i = 0; _i < 2; ++_i) \
;         __builtin_amdgcn_global_load_lds((const unsigned*)((const char*)(gbase) + (voff)[_i]), (LAS unsigned*)(lds + (bufoff) + ldsw + _i * 8192), 16, 0, 0); } while (0)
; #define PG8_LDA(dst, b, h) do { _Pragma("unroll") for (int m = 0; m < 4; ++m) _Pragma("unroll") for (int k = 0; k < 2; ++k) dst[m][k] = *(const LAS bf16x8*)(lds + PG8_SA(b, h) + aoff + m * 2048 + k * 1024); } while (0)
; #define PG8_LDB(dst, b, h) do { _Pragma("unroll") for (int n = 0; n < 2; ++n) _Pragma("unroll") for (int k = 0; k < 2; ++k) dst[n][k] = *(const LAS bf16x8*)(lds + PG8_SB(b, h) + boff + n * 2048 + k * 1024); } while (0)
; #define PG8_MMA(ai, bj, At, Bt) do { __builtin_amdgcn_s_setprio(1); _Pragma("unroll") for (int m = 0; m < 4; ++m) _Pragma("unroll") for (int n = 0; n < 2; ++n) _Pragma("unroll") for (int k = 0; k < 2; ++k) \
;         acc[ai][bj][m][n] = __builtin_amdgcn_mfma_f32_16x16x32_bf16(Bt[n][k], At[m][k], acc[ai][bj][m][n], 0, 0, 0); __builtin_amdgcn_s_setprio(0); } while (0)
; #define PG8_WAIT_L(n) asm volatile("s_waitcnt lgkmcnt(" #n ")" ::: "memory")
; #define PG8_BAR __builtin_amdgcn_s_barrier()
; #define PG8_SCHED __builtin_amdgcn_sched_barrier(0)
; template <class Epi, class Sched>
; DI void gemm_phase(LAS unsigned char* lds, const Gemm g, const Sched& S, const Epi& E) {
;     ...
;             PG8_LDB(B0, 0, 0); PG8_SCHED; PG8_LDA(At, 0, 0); PG8_STAGE(PG8_SA(1, 1), a1 + hstep, voffA);
;             PG8_WAIT_L(8); PG8_BAR; PG8_WAIT_L(0); PG8_MMA(0, 0, At, B0); PG8_BAR; PG8_SCHED;
;             PG8_LDB(B1, 0, 1); PG8_STAGE(PG8_SB(0, 0), b2, voffB);
;             PG8_BAR; PG8_WAIT_L(0); PG8_MMA(0, 1, At, B1); PG8_BAR;
;             PG8_LDA(At, 0, 1); PG8_STAGE(PG8_SA(0, 0), a2, voffA);
;             PG8_BAR; PG8_WAIT_L(0); PG8_MMA(1, 0, At, B0); PG8_BAR; PG8_SCHED;
.LBB0_1190:
	ds_read_b128 v[152:155], v149
	ds_read_b128 v[156:159], v149 offset:1024
	ds_read_b128 v[168:171], v149 offset:2048
	ds_read_b128 v[172:175], v149 offset:3072
	s_add_u32 s24, s22, 0xfffc0080
	s_addc_u32 s25, s23, -1
	s_cmp_eq_u32 s43, 12
	s_cselect_b32 s27, s17, s25
	s_cselect_b32 s26, s39, s24
	s_cselect_b32 s25, s11, s42
	s_cselect_b32 s24, s40, s41
	v_lshl_add_u64 v[160:161], s[22:23], 0, v[138:139]
	s_add_i32 m0, s9, 0xc000
	ds_read_b128 v[176:179], v150
	ds_read_b128 v[180:183], v150 offset:1024
	ds_read_b128 v[184:187], v150 offset:2048
	ds_read_b128 v[188:191], v150 offset:3072
	ds_read_b128 v[192:195], v150 offset:4096
	ds_read_b128 v[198:201], v150 offset:5120
	ds_read_b128 v[202:205], v150 offset:6144
	ds_read_b128 v[206:209], v150 offset:7168
	global_load_lds_dwordx4 v[160:161], off
	v_lshl_add_u64 v[160:161], s[22:23], 0, v[140:141]
	s_add_i32 m0, s9, 0xe000
	s_nop 0
	global_load_lds_dwordx4 v[160:161], off
	s_waitcnt lgkmcnt(8)
	s_barrier
	s_waitcnt lgkmcnt(0)
	s_setprio 1
	s_waitcnt lgkmcnt(0)
	v_mfma_f32_16x16x32_bf16 v[126:129], v[152:155], v[176:179], v[126:129]
	v_mfma_f32_16x16x32_bf16 v[122:125], v[168:171], v[176:179], v[122:125]
	v_mfma_f32_16x16x32_bf16 v[118:121], v[152:155], v[184:187], v[118:121]
	v_mfma_f32_16x16x32_bf16 v[114:117], v[168:171], v[184:187], v[114:117]
	v_mfma_f32_16x16x32_bf16 v[102:105], v[152:155], v[192:195], v[102:105]
	v_mfma_f32_16x16x32_bf16 v[98:101], v[168:171], v[192:195], v[98:101]
	v_mfma_f32_16x16x32_bf16 v[86:89], v[152:155], v[202:205], v[86:89]
	v_mfma_f32_16x16x32_bf16 v[82:85], v[168:171], v[202:205], v[82:85]
	v_mfma_f32_16x16x32_bf16 v[126:129], v[156:159], v[180:183], v[126:129]
	v_mfma_f32_16x16x32_bf16 v[122:125], v[172:175], v[180:183], v[122:125]
	v_mfma_f32_16x16x32_bf16 v[118:121], v[156:159], v[188:191], v[118:121]
	v_mfma_f32_16x16x32_bf16 v[114:117], v[172:175], v[188:191], v[114:117]
	v_mfma_f32_16x16x32_bf16 v[102:105], v[156:159], v[198:201], v[102:105]
	v_mfma_f32_16x16x32_bf16 v[98:101], v[172:175], v[198:201], v[98:101]
	v_mfma_f32_16x16x32_bf16 v[86:89], v[156:159], v[206:209], v[86:89]
	v_mfma_f32_16x16x32_bf16 v[82:85], v[172:175], v[206:209], v[82:85]
	s_setprio 0
	s_barrier
	s_add_i32 s47, s35, s12
	v_lshl_add_u64 v[160:161], s[24:25], 0, v[134:135]
	s_mov_b32 m0, s47
	ds_read_b128 v[210:213], v151
	ds_read_b128 v[214:217], v151 offset:1024
	ds_read_b128 v[218:221], v151 offset:2048
	ds_read_b128 v[222:225], v151 offset:3072
	global_load_lds_dwordx4 v[160:161], off
	v_lshl_add_u64 v[226:227], s[24:25], 0, v[130:131]
	s_add_i32 m0, s47, 0x2000
	s_nop 0
	global_load_lds_dwordx4 v[226:227], off
	s_barrier
	s_waitcnt lgkmcnt(0)
	s_setprio 1
	s_waitcnt lgkmcnt(0)
	v_mfma_f32_16x16x32_bf16 v[110:113], v[210:213], v[176:179], v[110:113]
	v_mfma_f32_16x16x32_bf16 v[106:109], v[218:221], v[176:179], v[106:109]
	v_mfma_f32_16x16x32_bf16 v[94:97], v[210:213], v[184:187], v[94:97]
	v_mfma_f32_16x16x32_bf16 v[90:93], v[218:221], v[184:187], v[90:93]
	v_mfma_f32_16x16x32_bf16 v[78:81], v[210:213], v[192:195], v[78:81]
	v_mfma_f32_16x16x32_bf16 v[74:77], v[218:221], v[192:195], v[74:77]
	v_mfma_f32_16x16x32_bf16 v[70:73], v[210:213], v[202:205], v[70:73]
	v_mfma_f32_16x16x32_bf16 v[66:69], v[218:221], v[202:205], v[66:69]
	v_mfma_f32_16x16x32_bf16 v[110:113], v[214:217], v[180:183], v[110:113]
	v_mfma_f32_16x16x32_bf16 v[106:109], v[222:225], v[180:183], v[106:109]
	v_mfma_f32_16x16x32_bf16 v[94:97], v[214:217], v[188:191], v[94:97]
	v_mfma_f32_16x16x32_bf16 v[90:93], v[222:225], v[188:191], v[90:93]
	v_mfma_f32_16x16x32_bf16 v[78:81], v[214:217], v[198:201], v[78:81]
	v_mfma_f32_16x16x32_bf16 v[74:77], v[222:225], v[198:201], v[74:77]
	v_mfma_f32_16x16x32_bf16 v[70:73], v[214:217], v[206:209], v[70:73]
	v_mfma_f32_16x16x32_bf16 v[66:69], v[222:225], v[206:209], v[66:69]
	s_setprio 0
	s_mov_b32 m0, s9
	v_lshl_add_u64 v[228:229], s[26:27], 0, v[136:137]
	s_barrier
	ds_read_b128 v[176:179], v150 offset:16384
	ds_read_b128 v[180:183], v150 offset:17408
	ds_read_b128 v[184:187], v150 offset:18432
	ds_read_b128 v[188:191], v150 offset:19456
	ds_read_b128 v[192:195], v150 offset:20480
	ds_read_b128 v[198:201], v150 offset:21504
	ds_read_b128 v[202:205], v150 offset:22528
	ds_read_b128 v[206:209], v150 offset:23552
	global_load_lds_dwordx4 v[228:229], off
	v_lshl_add_u64 v[230:231], s[26:27], 0, v[132:133]
	s_mov_b32 m0, s28
	s_nop 0
	global_load_lds_dwordx4 v[230:231], off
	s_barrier
	s_waitcnt lgkmcnt(0)
	s_setprio 1
	s_waitcnt lgkmcnt(0)
	v_mfma_f32_16x16x32_bf16 v[62:65], v[152:155], v[176:179], v[62:65]
	v_mfma_f32_16x16x32_bf16 v[58:61], v[168:171], v[176:179], v[58:61]
	v_mfma_f32_16x16x32_bf16 v[54:57], v[152:155], v[184:187], v[54:57]
	v_mfma_f32_16x16x32_bf16 v[50:53], v[168:171], v[184:187], v[50:53]
	v_mfma_f32_16x16x32_bf16 v[38:41], v[152:155], v[192:195], v[38:41]
	v_mfma_f32_16x16x32_bf16 v[34:37], v[168:171], v[192:195], v[34:37]
	v_mfma_f32_16x16x32_bf16 v[22:25], v[152:155], v[202:205], v[22:25]
	v_mfma_f32_16x16x32_bf16 v[18:21], v[168:171], v[202:205], v[18:21]
	v_mfma_f32_16x16x32_bf16 v[62:65], v[156:159], v[180:183], v[62:65]
	v_mfma_f32_16x16x32_bf16 v[58:61], v[172:175], v[180:183], v[58:61]
	v_mfma_f32_16x16x32_bf16 v[54:57], v[156:159], v[188:191], v[54:57]
	v_mfma_f32_16x16x32_bf16 v[50:53], v[172:175], v[188:191], v[50:53]
	v_mfma_f32_16x16x32_bf16 v[38:41], v[156:159], v[198:201], v[38:41]
	v_mfma_f32_16x16x32_bf16 v[34:37], v[172:175], v[198:201], v[34:37]
	v_mfma_f32_16x16x32_bf16 v[22:25], v[156:159], v[206:209], v[22:25]
	v_mfma_f32_16x16x32_bf16 v[18:21], v[172:175], v[206:209], v[18:21]
	s_setprio 0
	s_barrier
; #define PG8_STAGE(bufoff, gbase, voff) do { _Pragma("unroll") for (int _i = 0; _i < 2; ++_i) \
;         __builtin_amdgcn_global_load_lds((const unsigned*)((const char*)(gbase) + (voff)[_i]), (LAS unsigned*)(lds + (bufoff) + ldsw + _i * 8192), 16, 0, 0); } while (0)
; #define PG8_LDA(dst, b, h) do { _Pragma("unroll") for (int m = 0; m < 4; ++m) _Pragma("unroll") for (int k = 0; k < 2; ++k) dst[m][k] = *(const LAS bf16x8*)(lds + PG8_SA(b, h) + aoff + m * 2048 + k * 1024); } while (0)
; #define PG8_LDB(dst, b, h) do { _Pragma("unroll") for (int n = 0; n < 2; ++n) _Pragma("unroll") for (int k = 0; k < 2; ++k) dst[n][k] = *(const LAS bf16x8*)(lds + PG8_SB(b, h) + boff + n * 2048 + k * 1024); } while (0)
; #define PG8_MMA(ai, bj, At, Bt) do { __builtin_amdgcn_s_setprio(1); _Pragma("unroll") for (int m = 0; m < 4; ++m) _Pragma("unroll") for (int n = 0; n < 2; ++n) _Pragma("unroll") for (int k = 0; k < 2; ++k) \
;         acc[ai][bj][m][n] = __builtin_amdgcn_mfma_f32_16x16x32_bf16(Bt[n][k], At[m][k], acc[ai][bj][m][n], 0, 0, 0); __builtin_amdgcn_s_setprio(0); } while (0)
; #define PG8_WAIT_V(n) asm volatile("s_waitcnt vmcnt(" #n ")" ::: "memory")
; #define PG8_WAIT_L(n) asm volatile("s_waitcnt lgkmcnt(" #n ")" ::: "memory")
; #define PG8_BAR __builtin_amdgcn_s_barrier()
; #define PG8_SCHED __builtin_amdgcn_sched_barrier(0)
; template <class Epi, class Sched>
; DI void gemm_phase(LAS unsigned char* lds, const Gemm g, const Sched& S, const Epi& E) {
;     ...
;             PG8_STAGE(PG8_SB(0, 1), b2 + hstep, voffB);
;             PG8_WAIT_V(6); PG8_BAR; PG8_MMA(1, 1, At, B1); PG8_BAR;
;             PG8_LDB(B0, 1, 0); PG8_SCHED; PG8_LDA(At, 1, 0); PG8_STAGE(PG8_SA(0, 1), a2 + hstep, voffA);
;             PG8_WAIT_L(8); PG8_BAR; PG8_WAIT_L(0); PG8_MMA(0, 0, At, B0); PG8_BAR; PG8_SCHED;
;             PG8_LDB(B1, 1, 1); PG8_STAGE(PG8_SB(1, 0), b3, voffB);
;             PG8_BAR; PG8_WAIT_L(0); PG8_MMA(0, 1, At, B1); PG8_BAR;
;             PG8_LDA(At, 1, 1); PG8_STAGE(PG8_SA(1, 0), a3, voffA);
;             PG8_BAR; PG8_WAIT_L(0); PG8_MMA(1, 0, At, B0); PG8_BAR; PG8_SCHED;
	s_add_u32 s54, s24, 0x10000
	s_addc_u32 s55, s25, 0
	s_add_i32 s47, s36, s12
	v_lshl_add_u64 v[152:153], s[54:55], 0, v[134:135]
	s_mov_b32 m0, s47
	s_nop 0
	global_load_lds_dwordx4 v[152:153], off
	v_lshl_add_u64 v[152:153], s[54:55], 0, v[130:131]
	s_add_i32 m0, s47, 0x2000
	s_nop 0
	global_load_lds_dwordx4 v[152:153], off
	s_waitcnt vmcnt(6)
	s_barrier
	s_setprio 1
	v_mfma_f32_16x16x32_bf16 v[46:49], v[210:213], v[176:179], v[46:49]
	v_mfma_f32_16x16x32_bf16 v[42:45], v[218:221], v[176:179], v[42:45]
	v_mfma_f32_16x16x32_bf16 v[30:33], v[210:213], v[184:187], v[30:33]
	v_mfma_f32_16x16x32_bf16 v[26:29], v[218:221], v[184:187], v[26:29]
	v_mfma_f32_16x16x32_bf16 v[14:17], v[210:213], v[192:195], v[14:17]
	v_mfma_f32_16x16x32_bf16 v[10:13], v[218:221], v[192:195], v[10:13]
	v_mfma_f32_16x16x32_bf16 v[6:9], v[210:213], v[202:205], v[6:9]
	v_mfma_f32_16x16x32_bf16 v[2:5], v[218:221], v[202:205], v[2:5]
	v_mfma_f32_16x16x32_bf16 v[46:49], v[214:217], v[180:183], v[46:49]
	v_mfma_f32_16x16x32_bf16 v[42:45], v[222:225], v[180:183], v[42:45]
	v_mfma_f32_16x16x32_bf16 v[30:33], v[214:217], v[188:191], v[30:33]
	v_mfma_f32_16x16x32_bf16 v[26:29], v[222:225], v[188:191], v[26:29]
	v_mfma_f32_16x16x32_bf16 v[14:17], v[214:217], v[198:201], v[14:17]
	v_mfma_f32_16x16x32_bf16 v[10:13], v[222:225], v[198:201], v[10:13]
	v_mfma_f32_16x16x32_bf16 v[6:9], v[214:217], v[206:209], v[6:9]
	v_mfma_f32_16x16x32_bf16 v[2:5], v[222:225], v[206:209], v[2:5]
	s_setprio 0
	s_add_i32 s47, 0, 0x18000
	v_add_u32_e32 v165, s47, v147
	s_barrier
	ds_read_b128 v[152:155], v165
	ds_read_b128 v[156:159], v165 offset:1024
	ds_read_b128 v[168:171], v165 offset:2048
	ds_read_b128 v[172:175], v165 offset:3072
	s_add_u32 s26, s26, 0x40000
	s_addc_u32 s27, s27, 0
	s_mov_b32 m0, s29
	v_lshl_add_u64 v[210:211], s[26:27], 0, v[136:137]
	ds_read_b128 v[176:179], v150 offset:32768
	ds_read_b128 v[180:183], v150 offset:33792
	ds_read_b128 v[184:187], v150 offset:34816
	ds_read_b128 v[188:191], v150 offset:35840
	ds_read_b128 v[192:195], v150 offset:36864
	ds_read_b128 v[198:201], v150 offset:37888
	ds_read_b128 v[202:205], v150 offset:38912
	ds_read_b128 v[206:209], v150 offset:39936
	global_load_lds_dwordx4 v[210:211], off
	v_lshl_add_u64 v[210:211], s[26:27], 0, v[132:133]
	s_mov_b32 m0, s30
	s_nop 0
	global_load_lds_dwordx4 v[210:211], off
	s_waitcnt lgkmcnt(8)
	s_barrier
	s_waitcnt lgkmcnt(0)
	s_setprio 1
	s_waitcnt lgkmcnt(0)
	v_mfma_f32_16x16x32_bf16 v[126:129], v[152:155], v[176:179], v[126:129]
	v_mfma_f32_16x16x32_bf16 v[122:125], v[168:171], v[176:179], v[122:125]
	v_mfma_f32_16x16x32_bf16 v[118:121], v[152:155], v[184:187], v[118:121]
	v_mfma_f32_16x16x32_bf16 v[114:117], v[168:171], v[184:187], v[114:117]
	v_mfma_f32_16x16x32_bf16 v[102:105], v[152:155], v[192:195], v[102:105]
	v_mfma_f32_16x16x32_bf16 v[98:101], v[168:171], v[192:195], v[98:101]
	v_mfma_f32_16x16x32_bf16 v[86:89], v[152:155], v[202:205], v[86:89]
	v_mfma_f32_16x16x32_bf16 v[82:85], v[168:171], v[202:205], v[82:85]
	v_mfma_f32_16x16x32_bf16 v[126:129], v[156:159], v[180:183], v[126:129]
	v_mfma_f32_16x16x32_bf16 v[122:125], v[172:175], v[180:183], v[122:125]
	v_mfma_f32_16x16x32_bf16 v[118:121], v[156:159], v[188:191], v[118:121]
	v_mfma_f32_16x16x32_bf16 v[114:117], v[172:175], v[188:191], v[114:117]
	v_mfma_f32_16x16x32_bf16 v[102:105], v[156:159], v[198:201], v[102:105]
	v_mfma_f32_16x16x32_bf16 v[98:101], v[172:175], v[198:201], v[98:101]
	v_mfma_f32_16x16x32_bf16 v[86:89], v[156:159], v[206:209], v[86:89]
	v_mfma_f32_16x16x32_bf16 v[82:85], v[172:175], v[206:209], v[82:85]
	s_setprio 0
	s_barrier
	s_add_i32 s26, 0, 0x1c000
	s_add_i32 s27, s47, s12
	v_add_u32_e32 v165, s26, v147
	v_lshl_add_u64 v[160:161], v[160:161], 0, s[6:7]
	s_mov_b32 m0, s27
	ds_read_b128 v[210:213], v165
	ds_read_b128 v[214:217], v165 offset:1024
	ds_read_b128 v[218:221], v165 offset:2048
	ds_read_b128 v[222:225], v165 offset:3072
	global_load_lds_dwordx4 v[160:161], off
	v_lshl_add_u64 v[160:161], v[226:227], 0, s[6:7]
	s_add_i32 m0, s27, 0x2000
	s_nop 0
	global_load_lds_dwordx4 v[160:161], off
	s_barrier
	s_waitcnt lgkmcnt(0)
	s_setprio 1
	s_waitcnt lgkmcnt(0)
	v_mfma_f32_16x16x32_bf16 v[110:113], v[210:213], v[176:179], v[110:113]
	v_mfma_f32_16x16x32_bf16 v[106:109], v[218:221], v[176:179], v[106:109]
	v_mfma_f32_16x16x32_bf16 v[94:97], v[210:213], v[184:187], v[94:97]
	v_mfma_f32_16x16x32_bf16 v[90:93], v[218:221], v[184:187], v[90:93]
	v_mfma_f32_16x16x32_bf16 v[78:81], v[210:213], v[192:195], v[78:81]
	v_mfma_f32_16x16x32_bf16 v[74:77], v[218:221], v[192:195], v[74:77]
	v_mfma_f32_16x16x32_bf16 v[70:73], v[210:213], v[202:205], v[70:73]
	v_mfma_f32_16x16x32_bf16 v[66:69], v[218:221], v[202:205], v[66:69]
	v_mfma_f32_16x16x32_bf16 v[110:113], v[214:217], v[180:183], v[110:113]
	v_mfma_f32_16x16x32_bf16 v[106:109], v[222:225], v[180:183], v[106:109]
	v_mfma_f32_16x16x32_bf16 v[94:97], v[214:217], v[188:191], v[94:97]
	v_mfma_f32_16x16x32_bf16 v[90:93], v[222:225], v[188:191], v[90:93]
	v_mfma_f32_16x16x32_bf16 v[78:81], v[214:217], v[198:201], v[78:81]
	v_mfma_f32_16x16x32_bf16 v[74:77], v[222:225], v[198:201], v[74:77]
	v_mfma_f32_16x16x32_bf16 v[70:73], v[214:217], v[206:209], v[70:73]
	v_mfma_f32_16x16x32_bf16 v[66:69], v[222:225], v[206:209], v[66:69]
	s_setprio 0
	s_mov_b32 m0, s33
	v_lshl_add_u64 v[160:161], v[228:229], 0, s[6:7]
	s_barrier
	ds_read_b128 v[176:179], v150 offset:49152
	ds_read_b128 v[180:183], v150 offset:50176
	ds_read_b128 v[184:187], v150 offset:51200
	ds_read_b128 v[188:191], v150 offset:52224
	ds_read_b128 v[192:195], v150 offset:53248
	ds_read_b128 v[198:201], v150 offset:54272
	ds_read_b128 v[202:205], v150 offset:55296
	ds_read_b128 v[206:209], v150 offset:56320
	global_load_lds_dwordx4 v[160:161], off
	v_lshl_add_u64 v[160:161], v[230:231], 0, s[6:7]
	s_mov_b32 m0, s34
	s_nop 0
	global_load_lds_dwordx4 v[160:161], off
	s_barrier
; DI unsigned pk_bf16(float a, float b) { f32x2 v = {a, b}; bf2_t r = __builtin_convertvector(v, bf2_t); return __builtin_bit_cast(unsigned, r); }
; #define PG8_STAGE(bufoff, gbase, voff) do { _Pragma("unroll") for (int _i = 0; _i < 2; ++_i) \
;         __builtin_amdgcn_global_load_lds((const unsigned*)((const char*)(gbase) + (voff)[_i]), (LAS unsigned*)(lds + (bufoff) + ldsw + _i * 8192), 16, 0, 0); } while (0)
; #define PG8_MMA(ai, bj, At, Bt) do { __builtin_amdgcn_s_setprio(1); _Pragma("unroll") for (int m = 0; m < 4; ++m) _Pragma("unroll") for (int n = 0; n < 2; ++n) _Pragma("unroll") for (int k = 0; k < 2; ++k) \
;         acc[ai][bj][m][n] = __builtin_amdgcn_mfma_f32_16x16x32_bf16(Bt[n][k], At[m][k], acc[ai][bj][m][n], 0, 0, 0); __builtin_amdgcn_s_setprio(0); } while (0)
; #define PG8_WAIT_V(n) asm volatile("s_waitcnt vmcnt(" #n ")" ::: "memory")
; #define PG8_WAIT_L(n) asm volatile("s_waitcnt lgkmcnt(" #n ")" ::: "memory")
; #define PG8_BAR __builtin_amdgcn_s_barrier()
; #define PG8_SCHED __builtin_amdgcn_sched_barrier(0)
;     DI void operator()(const f32x4 (&acc)[2][2][4][2], const Unit& u, int wr, int wc, int fr, int fq) const {
;         const int row0 = u.pm * BM + wr * 64 + fr, col0 = u.pn * BM + wc * 32 + 8 * fq;
; #pragma unroll
;         for (int ai = 0; ai < 2; ++ai)
; #pragma unroll
;             for (int m = 0; m < 4; ++m) { bf16_t* rowp = O + (size_t)(row0 + ai * HALF + m * 16) * ldc + col0;
; #pragma unroll
;                 for (int bj = 0; bj < 2; ++bj) { const f32x4 v0 = acc[ai][bj][m][0], v1 = acc[ai][bj][m][1];
;                     u32x4 w; w.x = pk_bf16(v0[0], v0[1]); w.y = pk_bf16(v0[2], v0[3]); w.z = pk_bf16(v1[0], v1[1]); w.w = pk_bf16(v1[2], v1[3]);
;                     *(u32x4*)(rowp + bj * HALF) = w; } }
; template <class Epi, class Sched>
; DI void gemm_phase(LAS unsigned char* lds, const Gemm g, const Sched& S, const Epi& E) {
;     ...
;             PG8_BAR; PG8_WAIT_L(0); PG8_MMA(1, 0, At, B0); PG8_BAR; PG8_SCHED;
;             PG8_STAGE(PG8_SB(1, 1), b3 + hstep, voffB);
;             PG8_WAIT_V(6); PG8_BAR; PG8_MMA(1, 1, At, B1); PG8_BAR;
	s_waitcnt lgkmcnt(0)
	s_setprio 1
	s_waitcnt lgkmcnt(0)
	v_mfma_f32_16x16x32_bf16 v[62:65], v[152:155], v[176:179], v[62:65]
	v_mfma_f32_16x16x32_bf16 v[58:61], v[168:171], v[176:179], v[58:61]
	v_mfma_f32_16x16x32_bf16 v[54:57], v[152:155], v[184:187], v[54:57]
	v_mfma_f32_16x16x32_bf16 v[50:53], v[168:171], v[184:187], v[50:53]
	v_mfma_f32_16x16x32_bf16 v[38:41], v[152:155], v[192:195], v[38:41]
	v_mfma_f32_16x16x32_bf16 v[34:37], v[168:171], v[192:195], v[34:37]
	v_mfma_f32_16x16x32_bf16 v[22:25], v[152:155], v[202:205], v[22:25]
	v_mfma_f32_16x16x32_bf16 v[18:21], v[168:171], v[202:205], v[18:21]
	v_mfma_f32_16x16x32_bf16 v[62:65], v[156:159], v[180:183], v[62:65]
	v_mfma_f32_16x16x32_bf16 v[58:61], v[172:175], v[180:183], v[58:61]
	v_mfma_f32_16x16x32_bf16 v[54:57], v[156:159], v[188:191], v[54:57]
	v_mfma_f32_16x16x32_bf16 v[50:53], v[172:175], v[188:191], v[50:53]
	v_mfma_f32_16x16x32_bf16 v[38:41], v[156:159], v[198:201], v[38:41]
	v_mfma_f32_16x16x32_bf16 v[34:37], v[172:175], v[198:201], v[34:37]
	v_mfma_f32_16x16x32_bf16 v[22:25], v[156:159], v[206:209], v[22:25]
	v_mfma_f32_16x16x32_bf16 v[18:21], v[172:175], v[206:209], v[18:21]
	s_setprio 0
	s_barrier
	s_add_u32 s24, s24, 0x10080
	s_addc_u32 s25, s25, 0
	s_add_i32 s26, s26, s12
	v_lshl_add_u64 v[152:153], s[24:25], 0, v[134:135]
	s_mov_b32 m0, s26
	s_nop 0
	global_load_lds_dwordx4 v[152:153], off
	v_lshl_add_u64 v[152:153], s[24:25], 0, v[130:131]
	s_add_i32 m0, s26, 0x2000
	s_nop 0
	global_load_lds_dwordx4 v[152:153], off
	s_waitcnt vmcnt(6)
	s_barrier
	s_setprio 1
	v_mfma_f32_16x16x32_bf16 v[46:49], v[210:213], v[176:179], v[46:49]
	v_mfma_f32_16x16x32_bf16 v[42:45], v[218:221], v[176:179], v[42:45]
	v_mfma_f32_16x16x32_bf16 v[30:33], v[210:213], v[184:187], v[30:33]
	v_mfma_f32_16x16x32_bf16 v[26:29], v[218:221], v[184:187], v[26:29]
	v_mfma_f32_16x16x32_bf16 v[14:17], v[210:213], v[192:195], v[14:17]
	v_mfma_f32_16x16x32_bf16 v[10:13], v[218:221], v[192:195], v[10:13]
	v_mfma_f32_16x16x32_bf16 v[6:9], v[210:213], v[202:205], v[6:9]
	v_mfma_f32_16x16x32_bf16 v[2:5], v[218:221], v[202:205], v[2:5]
	v_mfma_f32_16x16x32_bf16 v[46:49], v[214:217], v[180:183], v[46:49]
	v_mfma_f32_16x16x32_bf16 v[42:45], v[222:225], v[180:183], v[42:45]
	v_mfma_f32_16x16x32_bf16 v[30:33], v[214:217], v[188:191], v[30:33]
	v_mfma_f32_16x16x32_bf16 v[26:29], v[222:225], v[188:191], v[26:29]
	v_mfma_f32_16x16x32_bf16 v[14:17], v[214:217], v[198:201], v[14:17]
	v_mfma_f32_16x16x32_bf16 v[10:13], v[222:225], v[198:201], v[10:13]
	v_mfma_f32_16x16x32_bf16 v[6:9], v[214:217], v[206:209], v[6:9]
	v_mfma_f32_16x16x32_bf16 v[2:5], v[222:225], v[206:209], v[2:5]
	s_setprio 0
	s_add_i32 s43, s43, 2
	s_add_u32 s22, s22, 0x100
	s_addc_u32 s23, s23, 0
	s_add_u32 s41, s41, 0x100
	s_addc_u32 s42, s42, 0
	s_cmp_gt_u32 s43, 13
	s_barrier
	s_cbranch_scc0 .LBB0_1190
	v_and_b32_e32 v152, 63, v1
	v_lshrrev_b32_e32 v240, 3, v152
	v_and_b32_e32 v153, 0xffffffc0, v146
	v_add_u32_e32 v153, v153, v240
	v_lshl_add_u32 v153, s8, 8, v153
	v_mul_u32_u24_e32 v153, 0x3000, v153
	v_and_b32_e32 v241, 0xffffffc0, v148
	v_lshl_or_b32 v241, s38, 8, v241
	v_and_b32_e32 v242, 7, v152
	v_lshlrev_b32_e32 v242, 4, v242
	v_lshl_add_u32 v244, v241, 1, v153
	v_add_u32_e32 v244, v244, v242
	v_and_b32_e32 v243, 3, v152
	v_lshlrev_b32_e32 v243, 4, v243
	v_bfe_u32 v242, v152, 2, 1
	v_lshl_or_b32 v243, v242, 3, v243
	v_or_b32_e32 v243, v243, v240
	v_lshlrev_b32_e32 v158, 2, v243
	v_add_u32_e32 v245, 0x18000, v244
	v_add_u32_e32 v246, 0x30000, v244
	v_add_u32_e32 v247, 0x48000, v244
	v_add_u32_e32 v248, 0x60000, v244
	v_add_u32_e32 v249, 0x78000, v244
	v_add_u32_e32 v250, 0x90000, v244
	v_add_u32_e32 v251, 0xa8000, v244
	v_add_u32_e32 v252, 0x180000, v244
	v_add_u32_e32 v253, 0x198000, v244
	v_add_u32_e32 v254, 0x1b0000, v244
	v_add_u32_e32 v255, 0x1c8000, v244
	v_add_u32_e32 v154, 0x1e0000, v244
	v_add_u32_e32 v155, 0x1f8000, v244
	v_add_u32_e32 v156, 0x210000, v244
	v_add_u32_e32 v157, 0x228000, v244
	s_and_b64 vcc, exec, s[4:5]
	s_mov_b32 s38, s10
	s_mov_b32 s8, s16
	s_mov_b64 s[24:25], s[20:21]
	s_mov_b64 s[22:23], s[18:19]
	v_cvt_pk_bf16_f32 v126, v126, v127
	v_cvt_pk_bf16_f32 v127, v128, v129
	v_cvt_pk_bf16_f32 v128, v122, v123
	v_cvt_pk_bf16_f32 v129, v124, v125
	v_cvt_pk_bf16_f32 v110, v110, v111
	v_cvt_pk_bf16_f32 v111, v112, v113
	v_cvt_pk_bf16_f32 v112, v106, v107
	v_cvt_pk_bf16_f32 v113, v108, v109
	v_mov_b32_dpp v240, v126 row_ror:8 row_mask:0xf bank_mask:0xf
	v_mov_b32_dpp v241, v127 row_ror:8 row_mask:0xf bank_mask:0xf
	v_mov_b32_dpp v242, v128 row_ror:8 row_mask:0xf bank_mask:0xf
	v_mov_b32_dpp v243, v129 row_ror:8 row_mask:0xf bank_mask:0xf
	v_mov_b32_dpp v126, v110 row_ror:8 row_mask:0xf bank_mask:0xc
	v_mov_b32_dpp v127, v111 row_ror:8 row_mask:0xf bank_mask:0xc
	v_mov_b32_dpp v128, v112 row_ror:8 row_mask:0xf bank_mask:0xc
	v_mov_b32_dpp v129, v113 row_ror:8 row_mask:0xf bank_mask:0xc
	v_mov_b32_dpp v110, v240 quad_perm:[0,1,2,3] row_mask:0xf bank_mask:0x3
	v_mov_b32_dpp v111, v241 quad_perm:[0,1,2,3] row_mask:0xf bank_mask:0x3
	v_mov_b32_dpp v112, v242 quad_perm:[0,1,2,3] row_mask:0xf bank_mask:0x3
	v_mov_b32_dpp v113, v243 quad_perm:[0,1,2,3] row_mask:0xf bank_mask:0x3
	ds_bpermute_b32 v122, v158, v126
	ds_bpermute_b32 v123, v158, v127
	ds_bpermute_b32 v124, v158, v128
	ds_bpermute_b32 v125, v158, v129
	ds_bpermute_b32 v106, v158, v110
	ds_bpermute_b32 v107, v158, v111
	ds_bpermute_b32 v108, v158, v112
	ds_bpermute_b32 v109, v158, v113
	v_cvt_pk_bf16_f32 v118, v118, v119
	v_cvt_pk_bf16_f32 v119, v120, v121
	v_cvt_pk_bf16_f32 v120, v114, v115
	v_cvt_pk_bf16_f32 v121, v116, v117
	v_cvt_pk_bf16_f32 v94, v94, v95
	v_cvt_pk_bf16_f32 v95, v96, v97
	v_cvt_pk_bf16_f32 v96, v90, v91
	v_cvt_pk_bf16_f32 v97, v92, v93
	v_mov_b32_dpp v240, v118 row_ror:8 row_mask:0xf bank_mask:0xf
	v_mov_b32_dpp v241, v119 row_ror:8 row_mask:0xf bank_mask:0xf
	v_mov_b32_dpp v242, v120 row_ror:8 row_mask:0xf bank_mask:0xf
	v_mov_b32_dpp v243, v121 row_ror:8 row_mask:0xf bank_mask:0xf
	v_mov_b32_dpp v118, v94 row_ror:8 row_mask:0xf bank_mask:0xc
	v_mov_b32_dpp v119, v95 row_ror:8 row_mask:0xf bank_mask:0xc
	v_mov_b32_dpp v120, v96 row_ror:8 row_mask:0xf bank_mask:0xc
	v_mov_b32_dpp v121, v97 row_ror:8 row_mask:0xf bank_mask:0xc
	v_mov_b32_dpp v94, v240 quad_perm:[0,1,2,3] row_mask:0xf bank_mask:0x3
	v_mov_b32_dpp v95, v241 quad_perm:[0,1,2,3] row_mask:0xf bank_mask:0x3
	v_mov_b32_dpp v96, v242 quad_perm:[0,1,2,3] row_mask:0xf bank_mask:0x3
	v_mov_b32_dpp v97, v243 quad_perm:[0,1,2,3] row_mask:0xf bank_mask:0x3
	s_waitcnt lgkmcnt(0)
; DI unsigned pk_bf16(float a, float b) { f32x2 v = {a, b}; bf2_t r = __builtin_convertvector(v, bf2_t); return __builtin_bit_cast(unsigned, r); }
;     DI void operator()(const f32x4 (&acc)[2][2][4][2], const Unit& u, int wr, int wc, int fr, int fq) const {
;     ...
;             for (int m = 0; m < 4; ++m) { bf16_t* rowp = O + (size_t)(row0 + ai * HALF + m * 16) * ldc + col0;
; #pragma unroll
;                 for (int bj = 0; bj < 2; ++bj) { const f32x4 v0 = acc[ai][bj][m][0], v1 = acc[ai][bj][m][1];
;                     u32x4 w; w.x = pk_bf16(v0[0], v0[1]); w.y = pk_bf16(v0[2], v0[3]); w.z = pk_bf16(v1[0], v1[1]); w.w = pk_bf16(v1[2], v1[3]);
;                     *(u32x4*)(rowp + bj * HALF) = w; } }
	global_store_dwordx4 v244, v[122:125], s[86:87] nt
	global_store_dwordx4 v245, v[106:109], s[86:87] nt
	ds_bpermute_b32 v114, v158, v118
	ds_bpermute_b32 v115, v158, v119
	ds_bpermute_b32 v116, v158, v120
	ds_bpermute_b32 v117, v158, v121
	ds_bpermute_b32 v90, v158, v94
	ds_bpermute_b32 v91, v158, v95
	ds_bpermute_b32 v92, v158, v96
	ds_bpermute_b32 v93, v158, v97
	v_cvt_pk_bf16_f32 v102, v102, v103
	v_cvt_pk_bf16_f32 v103, v104, v105
	v_cvt_pk_bf16_f32 v104, v98, v99
	v_cvt_pk_bf16_f32 v105, v100, v101
	v_cvt_pk_bf16_f32 v78, v78, v79
	v_cvt_pk_bf16_f32 v79, v80, v81
	v_cvt_pk_bf16_f32 v80, v74, v75
	v_cvt_pk_bf16_f32 v81, v76, v77
	v_mov_b32_dpp v240, v102 row_ror:8 row_mask:0xf bank_mask:0xf
	v_mov_b32_dpp v241, v103 row_ror:8 row_mask:0xf bank_mask:0xf
	v_mov_b32_dpp v242, v104 row_ror:8 row_mask:0xf bank_mask:0xf
	v_mov_b32_dpp v243, v105 row_ror:8 row_mask:0xf bank_mask:0xf
	v_mov_b32_dpp v102, v78 row_ror:8 row_mask:0xf bank_mask:0xc
	v_mov_b32_dpp v103, v79 row_ror:8 row_mask:0xf bank_mask:0xc
	v_mov_b32_dpp v104, v80 row_ror:8 row_mask:0xf bank_mask:0xc
	v_mov_b32_dpp v105, v81 row_ror:8 row_mask:0xf bank_mask:0xc
	v_mov_b32_dpp v78, v240 quad_perm:[0,1,2,3] row_mask:0xf bank_mask:0x3
	v_mov_b32_dpp v79, v241 quad_perm:[0,1,2,3] row_mask:0xf bank_mask:0x3
	v_mov_b32_dpp v80, v242 quad_perm:[0,1,2,3] row_mask:0xf bank_mask:0x3
	v_mov_b32_dpp v81, v243 quad_perm:[0,1,2,3] row_mask:0xf bank_mask:0x3
	s_waitcnt lgkmcnt(0)
	global_store_dwordx4 v246, v[114:117], s[86:87] nt
	global_store_dwordx4 v247, v[90:93], s[86:87] nt
	ds_bpermute_b32 v98, v158, v102
	ds_bpermute_b32 v99, v158, v103
	ds_bpermute_b32 v100, v158, v104
	ds_bpermute_b32 v101, v158, v105
	ds_bpermute_b32 v74, v158, v78
	ds_bpermute_b32 v75, v158, v79
	ds_bpermute_b32 v76, v158, v80
	ds_bpermute_b32 v77, v158, v81
	v_cvt_pk_bf16_f32 v86, v86, v87
	v_cvt_pk_bf16_f32 v87, v88, v89
	v_cvt_pk_bf16_f32 v88, v82, v83
	v_cvt_pk_bf16_f32 v89, v84, v85
	v_cvt_pk_bf16_f32 v70, v70, v71
	v_cvt_pk_bf16_f32 v71, v72, v73
	v_cvt_pk_bf16_f32 v72, v66, v67
	v_cvt_pk_bf16_f32 v73, v68, v69
	v_mov_b32_dpp v240, v86 row_ror:8 row_mask:0xf bank_mask:0xf
	v_mov_b32_dpp v241, v87 row_ror:8 row_mask:0xf bank_mask:0xf
	v_mov_b32_dpp v242, v88 row_ror:8 row_mask:0xf bank_mask:0xf
	v_mov_b32_dpp v243, v89 row_ror:8 row_mask:0xf bank_mask:0xf
	v_mov_b32_dpp v86, v70 row_ror:8 row_mask:0xf bank_mask:0xc
	v_mov_b32_dpp v87, v71 row_ror:8 row_mask:0xf bank_mask:0xc
	v_mov_b32_dpp v88, v72 row_ror:8 row_mask:0xf bank_mask:0xc
	v_mov_b32_dpp v89, v73 row_ror:8 row_mask:0xf bank_mask:0xc
	v_mov_b32_dpp v70, v240 quad_perm:[0,1,2,3] row_mask:0xf bank_mask:0x3
	v_mov_b32_dpp v71, v241 quad_perm:[0,1,2,3] row_mask:0xf bank_mask:0x3
	v_mov_b32_dpp v72, v242 quad_perm:[0,1,2,3] row_mask:0xf bank_mask:0x3
	v_mov_b32_dpp v73, v243 quad_perm:[0,1,2,3] row_mask:0xf bank_mask:0x3
	s_waitcnt lgkmcnt(0)
	global_store_dwordx4 v248, v[98:101], s[86:87] nt
	global_store_dwordx4 v249, v[74:77], s[86:87] nt
	ds_bpermute_b32 v82, v158, v86
	ds_bpermute_b32 v83, v158, v87
	ds_bpermute_b32 v84, v158, v88
	ds_bpermute_b32 v85, v158, v89
	ds_bpermute_b32 v66, v158, v70
	ds_bpermute_b32 v67, v158, v71
	ds_bpermute_b32 v68, v158, v72
	ds_bpermute_b32 v69, v158, v73
	v_cvt_pk_bf16_f32 v62, v62, v63
	v_cvt_pk_bf16_f32 v63, v64, v65
	v_cvt_pk_bf16_f32 v64, v58, v59
	v_cvt_pk_bf16_f32 v65, v60, v61
	v_cvt_pk_bf16_f32 v46, v46, v47
	v_cvt_pk_bf16_f32 v47, v48, v49
	v_cvt_pk_bf16_f32 v48, v42, v43
	v_cvt_pk_bf16_f32 v49, v44, v45
	v_mov_b32_dpp v240, v62 row_ror:8 row_mask:0xf bank_mask:0xf
	v_mov_b32_dpp v241, v63 row_ror:8 row_mask:0xf bank_mask:0xf
	v_mov_b32_dpp v242, v64 row_ror:8 row_mask:0xf bank_mask:0xf
	v_mov_b32_dpp v243, v65 row_ror:8 row_mask:0xf bank_mask:0xf
	v_mov_b32_dpp v62, v46 row_ror:8 row_mask:0xf bank_mask:0xc
	v_mov_b32_dpp v63, v47 row_ror:8 row_mask:0xf bank_mask:0xc
	v_mov_b32_dpp v64, v48 row_ror:8 row_mask:0xf bank_mask:0xc
	v_mov_b32_dpp v65, v49 row_ror:8 row_mask:0xf bank_mask:0xc
	v_mov_b32_dpp v46, v240 quad_perm:[0,1,2,3] row_mask:0xf bank_mask:0x3
	v_mov_b32_dpp v47, v241 quad_perm:[0,1,2,3] row_mask:0xf bank_mask:0x3
	v_mov_b32_dpp v48, v242 quad_perm:[0,1,2,3] row_mask:0xf bank_mask:0x3
	v_mov_b32_dpp v49, v243 quad_perm:[0,1,2,3] row_mask:0xf bank_mask:0x3
	s_waitcnt lgkmcnt(0)
; DI unsigned pk_bf16(float a, float b) { f32x2 v = {a, b}; bf2_t r = __builtin_convertvector(v, bf2_t); return __builtin_bit_cast(unsigned, r); }
; #define PG8_WAIT_V(n) asm volatile("s_waitcnt vmcnt(" #n ")" ::: "memory")
; #define PG8_BAR __builtin_amdgcn_s_barrier()
;     DI void operator()(const f32x4 (&acc)[2][2][4][2], const Unit& u, int wr, int wc, int fr, int fq) const {
;     ...
;             for (int m = 0; m < 4; ++m) { bf16_t* rowp = O + (size_t)(row0 + ai * HALF + m * 16) * ldc + col0;
; #pragma unroll
;                 for (int bj = 0; bj < 2; ++bj) { const f32x4 v0 = acc[ai][bj][m][0], v1 = acc[ai][bj][m][1];
;                     u32x4 w; w.x = pk_bf16(v0[0], v0[1]); w.y = pk_bf16(v0[2], v0[3]); w.z = pk_bf16(v1[0], v1[1]); w.w = pk_bf16(v1[2], v1[3]);
;                     *(u32x4*)(rowp + bj * HALF) = w; } }
; template <class Epi, class Sched>
; DI void gemm_phase(LAS unsigned char* lds, const Gemm g, const Sched& S, const Epi& E) {
;     ...
;         if (!has_next) break;
; #pragma unroll
;         for (int a = 0; a < 2; ++a)
; #pragma unroll
;             for (int b = 0; b < 2; ++b)
; #pragma unroll
;                 for (int m = 0; m < 4; ++m)
; #pragma unroll
;                     for (int n = 0; n < 2; ++n) acc[a][b][m][n] = (f32x4){0.f, 0.f, 0.f, 0.f};
;         cur = nxt; cA = nA; cB = nB; ++ui;
;     }
;     PG8_WAIT_V(0);
;     if (wr == 0) PG8_BAR;
	global_store_dwordx4 v250, v[82:85], s[86:87] nt
	global_store_dwordx4 v251, v[66:69], s[86:87] nt
	ds_bpermute_b32 v58, v158, v62
	ds_bpermute_b32 v59, v158, v63
	ds_bpermute_b32 v60, v158, v64
	ds_bpermute_b32 v61, v158, v65
	ds_bpermute_b32 v42, v158, v46
	ds_bpermute_b32 v43, v158, v47
	ds_bpermute_b32 v44, v158, v48
	ds_bpermute_b32 v45, v158, v49
	v_cvt_pk_bf16_f32 v54, v54, v55
	v_cvt_pk_bf16_f32 v55, v56, v57
	v_cvt_pk_bf16_f32 v56, v50, v51
	v_cvt_pk_bf16_f32 v57, v52, v53
	v_cvt_pk_bf16_f32 v30, v30, v31
	v_cvt_pk_bf16_f32 v31, v32, v33
	v_cvt_pk_bf16_f32 v32, v26, v27
	v_cvt_pk_bf16_f32 v33, v28, v29
	v_mov_b32_dpp v240, v54 row_ror:8 row_mask:0xf bank_mask:0xf
	v_mov_b32_dpp v241, v55 row_ror:8 row_mask:0xf bank_mask:0xf
	v_mov_b32_dpp v242, v56 row_ror:8 row_mask:0xf bank_mask:0xf
	v_mov_b32_dpp v243, v57 row_ror:8 row_mask:0xf bank_mask:0xf
	v_mov_b32_dpp v54, v30 row_ror:8 row_mask:0xf bank_mask:0xc
	v_mov_b32_dpp v55, v31 row_ror:8 row_mask:0xf bank_mask:0xc
	v_mov_b32_dpp v56, v32 row_ror:8 row_mask:0xf bank_mask:0xc
	v_mov_b32_dpp v57, v33 row_ror:8 row_mask:0xf bank_mask:0xc
	v_mov_b32_dpp v30, v240 quad_perm:[0,1,2,3] row_mask:0xf bank_mask:0x3
	v_mov_b32_dpp v31, v241 quad_perm:[0,1,2,3] row_mask:0xf bank_mask:0x3
	v_mov_b32_dpp v32, v242 quad_perm:[0,1,2,3] row_mask:0xf bank_mask:0x3
	v_mov_b32_dpp v33, v243 quad_perm:[0,1,2,3] row_mask:0xf bank_mask:0x3
	s_waitcnt lgkmcnt(0)
	global_store_dwordx4 v252, v[58:61], s[86:87] nt
	global_store_dwordx4 v253, v[42:45], s[86:87] nt
	ds_bpermute_b32 v50, v158, v54
	ds_bpermute_b32 v51, v158, v55
	ds_bpermute_b32 v52, v158, v56
	ds_bpermute_b32 v53, v158, v57
	ds_bpermute_b32 v26, v158, v30
	ds_bpermute_b32 v27, v158, v31
	ds_bpermute_b32 v28, v158, v32
	ds_bpermute_b32 v29, v158, v33
	v_cvt_pk_bf16_f32 v38, v38, v39
	v_cvt_pk_bf16_f32 v39, v40, v41
	v_cvt_pk_bf16_f32 v40, v34, v35
	v_cvt_pk_bf16_f32 v41, v36, v37
	v_cvt_pk_bf16_f32 v14, v14, v15
	v_cvt_pk_bf16_f32 v15, v16, v17
	v_cvt_pk_bf16_f32 v16, v10, v11
	v_cvt_pk_bf16_f32 v17, v12, v13
	v_mov_b32_dpp v240, v38 row_ror:8 row_mask:0xf bank_mask:0xf
	v_mov_b32_dpp v241, v39 row_ror:8 row_mask:0xf bank_mask:0xf
	v_mov_b32_dpp v242, v40 row_ror:8 row_mask:0xf bank_mask:0xf
	v_mov_b32_dpp v243, v41 row_ror:8 row_mask:0xf bank_mask:0xf
	v_mov_b32_dpp v38, v14 row_ror:8 row_mask:0xf bank_mask:0xc
	v_mov_b32_dpp v39, v15 row_ror:8 row_mask:0xf bank_mask:0xc
	v_mov_b32_dpp v40, v16 row_ror:8 row_mask:0xf bank_mask:0xc
	v_mov_b32_dpp v41, v17 row_ror:8 row_mask:0xf bank_mask:0xc
	v_mov_b32_dpp v14, v240 quad_perm:[0,1,2,3] row_mask:0xf bank_mask:0x3
	v_mov_b32_dpp v15, v241 quad_perm:[0,1,2,3] row_mask:0xf bank_mask:0x3
	v_mov_b32_dpp v16, v242 quad_perm:[0,1,2,3] row_mask:0xf bank_mask:0x3
	v_mov_b32_dpp v17, v243 quad_perm:[0,1,2,3] row_mask:0xf bank_mask:0x3
	s_waitcnt lgkmcnt(0)
	global_store_dwordx4 v254, v[50:53], s[86:87] nt
	global_store_dwordx4 v255, v[26:29], s[86:87] nt
	ds_bpermute_b32 v34, v158, v38
	ds_bpermute_b32 v35, v158, v39
	ds_bpermute_b32 v36, v158, v40
	ds_bpermute_b32 v37, v158, v41
	ds_bpermute_b32 v10, v158, v14
	ds_bpermute_b32 v11, v158, v15
	ds_bpermute_b32 v12, v158, v16
	ds_bpermute_b32 v13, v158, v17
	v_cvt_pk_bf16_f32 v22, v22, v23
	v_cvt_pk_bf16_f32 v23, v24, v25
	v_cvt_pk_bf16_f32 v24, v18, v19
	v_cvt_pk_bf16_f32 v25, v20, v21
	v_cvt_pk_bf16_f32 v6, v6, v7
	v_cvt_pk_bf16_f32 v7, v8, v9
	v_cvt_pk_bf16_f32 v8, v2, v3
	v_cvt_pk_bf16_f32 v9, v4, v5
	v_mov_b32_dpp v240, v22 row_ror:8 row_mask:0xf bank_mask:0xf
	v_mov_b32_dpp v241, v23 row_ror:8 row_mask:0xf bank_mask:0xf
	v_mov_b32_dpp v242, v24 row_ror:8 row_mask:0xf bank_mask:0xf
	v_mov_b32_dpp v243, v25 row_ror:8 row_mask:0xf bank_mask:0xf
	v_mov_b32_dpp v22, v6 row_ror:8 row_mask:0xf bank_mask:0xc
	v_mov_b32_dpp v23, v7 row_ror:8 row_mask:0xf bank_mask:0xc
	v_mov_b32_dpp v24, v8 row_ror:8 row_mask:0xf bank_mask:0xc
	v_mov_b32_dpp v25, v9 row_ror:8 row_mask:0xf bank_mask:0xc
	v_mov_b32_dpp v6, v240 quad_perm:[0,1,2,3] row_mask:0xf bank_mask:0x3
	v_mov_b32_dpp v7, v241 quad_perm:[0,1,2,3] row_mask:0xf bank_mask:0x3
	v_mov_b32_dpp v8, v242 quad_perm:[0,1,2,3] row_mask:0xf bank_mask:0x3
	v_mov_b32_dpp v9, v243 quad_perm:[0,1,2,3] row_mask:0xf bank_mask:0x3
	s_waitcnt lgkmcnt(0)
	global_store_dwordx4 v154, v[34:37], s[86:87] nt
	global_store_dwordx4 v155, v[10:13], s[86:87] nt
	ds_bpermute_b32 v18, v158, v22
	ds_bpermute_b32 v19, v158, v23
	ds_bpermute_b32 v20, v158, v24
	ds_bpermute_b32 v21, v158, v25
	ds_bpermute_b32 v2, v158, v6
	ds_bpermute_b32 v3, v158, v7
	ds_bpermute_b32 v4, v158, v8
	ds_bpermute_b32 v5, v158, v9
	s_waitcnt lgkmcnt(0)
	global_store_dwordx4 v156, v[18:21], s[86:87] nt
	global_store_dwordx4 v157, v[2:5], s[86:87] nt
	s_cbranch_vccz .LBB0_1187
	s_waitcnt vmcnt(0)
	s_cmpk_gt_u32 s3, 0xff
	s_cbranch_scc1 .LBB0_1194
	s_barrier
